# stack + FFN-up/W_in tile scheduling block moved into the peeled iteration's load segments
# baseline (speedup 1.0000x reference)
; #define PG8_STAGE(bufoff, gbase, voff) do { _Pragma("unroll") for (int _i = 0; _i < 2; ++_i) \
;         __builtin_amdgcn_global_load_lds((const unsigned*)((const char*)(gbase) + (voff)[_i]), (LAS unsigned*)(lds + (bufoff) + ldsw + _i * 8192), 16, 0, 0); } while (0)
; #define PG8_LDA(dst, b, h) do { _Pragma("unroll") for (int m = 0; m < 4; ++m) _Pragma("unroll") for (int k = 0; k < 2; ++k) dst[m][k] = *(const LAS bf16x8*)(lds + PG8_SA(b, h) + aoff + m * 2048 + k * 1024); } while (0)
; #define PG8_LDB(dst, b, h) do { _Pragma("unroll") for (int n = 0; n < 2; ++n) _Pragma("unroll") for (int k = 0; k < 2; ++k) dst[n][k] = *(const LAS bf16x8*)(lds + PG8_SB(b, h) + boff + n * 2048 + k * 1024); } while (0)
; #define PG8_MMA(ai, bj, At, Bt) do { __builtin_amdgcn_s_setprio(1); _Pragma("unroll") for (int m = 0; m < 4; ++m) _Pragma("unroll") for (int n = 0; n < 2; ++n) _Pragma("unroll") for (int k = 0; k < 2; ++k) \
;         acc[ai][bj][m][n] = __builtin_amdgcn_mfma_f32_16x16x32_bf16(Bt[n][k], At[m][k], acc[ai][bj][m][n], 0, 0, 0); __builtin_amdgcn_s_setprio(0); } while (0)
; #define PG8_WAIT_V(n) asm volatile("s_waitcnt vmcnt(" #n ")" ::: "memory")
; #define PG8_WAIT_L(n) asm volatile("s_waitcnt lgkmcnt(" #n ")" ::: "memory")
; #define PG8_BAR __builtin_amdgcn_s_barrier()
; #define PG8_SCHED __builtin_amdgcn_sched_barrier(0)
;     DI bool next(int i, Unit& u) const {
;         const long L = (long)i * G + c; if (L >= total) return false;
;         u.g = (int)(L / nwg); int wgid = (int)(L % nwg);
;         { const int q = nwg / NXCD, r = nwg % NXCD, xcd = wgid % NXCD, off = wgid / NXCD; wgid = (xcd < r ? xcd * (q + 1) : r * (q + 1) + (xcd - r) * q) + off; }
; template <class Epi>
; DI void gemm_phase(LAS unsigned char* lds, const int wid, const Gemm g, const Order& S, const Epi& E) {
;     ...
;             PG8_LDB(B0, 0, 0); PG8_LDB(B1, 0, 1); PG8_SCHED; PG8_LDA(At, 0, 0); PG8_STAGE(PG8_SA(1, 1), a1 + hstepA, voffA);
;             PG8_WAIT_V(8); PG8_WAIT_L(0); PG8_BAR; PG8_MMA(0, 0, At, B0); PG8_MMA(0, 1, At, B1); PG8_BAR; PG8_SCHED;
;             PG8_LDA(At, 0, 1); PG8_STAGE(PG8_SB(0, 0), b2, voffB); PG8_STAGE(PG8_SB(0, 1), b2 + hstepB, voffB); PG8_STAGE(PG8_SA(0, 0), a2, voffA);
.LBB0_225:
.LBB0_227:
	s_add_u32 s42, s42, 0x40080
	s_addc_u32 s43, s43, 0
	s_add_u32 s61, s44, 0x100
	v_mov_b32_e32 v0, 0
	s_addc_u32 s62, s45, 0
	s_mov_b32 s63, -2
	s_lshl_b32 s74, s40, 8
	s_add_i32 s74, s74, s95
	v_mbcnt_lo_u32_b32 v244, -1, 0
	v_mbcnt_hi_u32_b32 v244, -1, v244
	v_and_or_b32 v244, v244, 15, s74
	v_ashrrev_i32_e32 v245, 31, v244
	v_lshl_add_u64 v[246:247], v[244:245], 2, s[12:13]
	global_load_dword v236, v[246:247], off
	global_load_dword v237, v[246:247], off offset:64
	global_load_dword v238, v[246:247], off offset:128
	global_load_dword v239, v[246:247], off offset:192
	global_load_dword v240, v[246:247], off offset:512
	global_load_dword v241, v[246:247], off offset:576
	global_load_dword v242, v[246:247], off offset:640
	global_load_dword v243, v[246:247], off offset:704
	ds_read_b128 v[164:167], v151
	ds_read_b128 v[168:171], v151 offset:1024
	ds_read_b128 v[172:175], v151 offset:2048
	ds_read_b128 v[176:179], v151 offset:3072
	ds_read_b128 v[180:183], v155
	ds_read_b128 v[184:187], v155 offset:1024
	ds_read_b128 v[188:191], v155 offset:2048
	ds_read_b128 v[192:195], v155 offset:3072
	s_add_u32 s44, s42, 0xfffc0080
	s_addc_u32 s45, s43, -1
	s_cmp_eq_u32 s63, 12
	s_cselect_b32 s47, s31, s45
	s_cselect_b32 s46, s59, s44
	s_cselect_b32 s45, s35, s62
	s_cselect_b32 s44, s60, s61
	v_lshl_add_u64 v[144:145], s[42:43], 0, v[136:137]
	s_add_i32 m0, s27, 0xc000
	ds_read_b128 v[196:199], v159
	ds_read_b128 v[200:203], v159 offset:1024
	ds_read_b128 v[204:207], v159 offset:2048
	ds_read_b128 v[208:211], v159 offset:3072
	ds_read_b128 v[216:219], v159 offset:4096
	ds_read_b128 v[220:223], v159 offset:5120
	ds_read_b128 v[224:227], v159 offset:6144
	ds_read_b128 v[228:231], v159 offset:7168
	global_load_lds_dwordx4 v[144:145], off
	v_lshl_add_u64 v[144:145], s[42:43], 0, v[138:139]
	s_add_i32 m0, s27, 0xe000
	s_nop 0
	global_load_lds_dwordx4 v[144:145], off
	s_waitcnt vmcnt(8)
	s_waitcnt lgkmcnt(0)
	s_barrier
	s_setprio 1
	v_mfma_f32_16x16x32_bf16 v[124:127], v[164:167], v[196:199], 0
	v_mfma_f32_16x16x32_bf16 v[120:123], v[172:175], v[196:199], 0
	v_mfma_f32_16x16x32_bf16 v[108:111], v[164:167], v[204:207], 0
	v_mfma_f32_16x16x32_bf16 v[104:107], v[172:175], v[204:207], 0
	v_mfma_f32_16x16x32_bf16 v[92:95], v[164:167], v[216:219], 0
	v_mfma_f32_16x16x32_bf16 v[88:91], v[172:175], v[216:219], 0
	v_mfma_f32_16x16x32_bf16 v[76:79], v[164:167], v[224:227], 0
	v_mfma_f32_16x16x32_bf16 v[72:75], v[172:175], v[224:227], 0
	v_mfma_f32_16x16x32_bf16 v[124:127], v[168:171], v[200:203], v[124:127]
	v_mfma_f32_16x16x32_bf16 v[120:123], v[176:179], v[200:203], v[120:123]
	v_mfma_f32_16x16x32_bf16 v[108:111], v[168:171], v[208:211], v[108:111]
	v_mfma_f32_16x16x32_bf16 v[104:107], v[176:179], v[208:211], v[104:107]
	v_mfma_f32_16x16x32_bf16 v[92:95], v[168:171], v[220:223], v[92:95]
	v_mfma_f32_16x16x32_bf16 v[88:91], v[176:179], v[220:223], v[88:91]
	v_mfma_f32_16x16x32_bf16 v[76:79], v[168:171], v[228:231], v[76:79]
	v_mfma_f32_16x16x32_bf16 v[72:75], v[176:179], v[228:231], v[72:75]
	v_mfma_f32_16x16x32_bf16 v[116:119], v[180:183], v[196:199], 0
	v_mfma_f32_16x16x32_bf16 v[112:115], v[188:191], v[196:199], 0
	v_mfma_f32_16x16x32_bf16 v[100:103], v[180:183], v[204:207], 0
	v_mfma_f32_16x16x32_bf16 v[96:99], v[188:191], v[204:207], 0
	v_mfma_f32_16x16x32_bf16 v[84:87], v[180:183], v[216:219], 0
	v_mfma_f32_16x16x32_bf16 v[80:83], v[188:191], v[216:219], 0
	v_mfma_f32_16x16x32_bf16 v[68:71], v[180:183], v[224:227], 0
	v_mfma_f32_16x16x32_bf16 v[64:67], v[188:191], v[224:227], 0
	v_mfma_f32_16x16x32_bf16 v[116:119], v[184:187], v[200:203], v[116:119]
	v_mfma_f32_16x16x32_bf16 v[112:115], v[192:195], v[200:203], v[112:115]
	v_mfma_f32_16x16x32_bf16 v[100:103], v[184:187], v[208:211], v[100:103]
	v_mfma_f32_16x16x32_bf16 v[96:99], v[192:195], v[208:211], v[96:99]
	v_mfma_f32_16x16x32_bf16 v[84:87], v[184:187], v[220:223], v[84:87]
	v_mfma_f32_16x16x32_bf16 v[80:83], v[192:195], v[220:223], v[80:83]
	v_mfma_f32_16x16x32_bf16 v[68:71], v[184:187], v[228:231], v[68:71]
	v_mfma_f32_16x16x32_bf16 v[64:67], v[192:195], v[228:231], v[64:67]
	s_setprio 0
	s_barrier
	s_add_i32 s64, s56, s94
	v_lshl_add_u64 v[144:145], s[44:45], 0, v[132:133]
	s_mov_b32 m0, s64
	ds_read_b128 v[196:199], v159 offset:16384
	ds_read_b128 v[200:203], v159 offset:17408
	ds_read_b128 v[204:207], v159 offset:18432
	ds_read_b128 v[208:211], v159 offset:19456
	ds_read_b128 v[216:219], v159 offset:20480
	ds_read_b128 v[220:223], v159 offset:21504
	ds_read_b128 v[224:227], v159 offset:22528
	ds_read_b128 v[228:231], v159 offset:23552
	global_load_lds_dwordx4 v[144:145], off
	s_add_i32 m0, s64, 0x2000
	s_add_u32 s64, s44, 0x40000
	v_lshl_add_u64 v[148:149], s[44:45], 0, v[128:129]
	s_addc_u32 s65, s45, 0
	s_add_i32 s66, s57, s94
	global_load_lds_dwordx4 v[148:149], off
	v_lshl_add_u64 v[152:153], s[64:65], 0, v[132:133]
	s_mov_b32 m0, s66
	v_lshl_add_u64 v[156:157], s[46:47], 0, v[130:131]
	global_load_lds_dwordx4 v[152:153], off
	v_lshl_add_u64 v[152:153], s[64:65], 0, v[128:129]
	s_add_i32 m0, s66, 0x2000
	s_nop 0
	global_load_lds_dwordx4 v[152:153], off
	v_lshl_add_u64 v[152:153], s[46:47], 0, v[134:135]
	s_mov_b32 m0, s27
	s_nop 0
	global_load_lds_dwordx4 v[152:153], off
	s_mov_b32 m0, s41
	s_nop 0
	global_load_lds_dwordx4 v[156:157], off
	s_add_i32 s50, s50, 1
	s_mul_i32 s6, s50, s53
	s_mul_hi_u32 s7, s50, s54
	s_add_i32 s7, s7, s6
	s_mul_i32 s6, s50, s54
	s_add_u32 s36, s6, s2
	s_addc_u32 s37, s7, s3
	v_cmp_lt_i64_e64 s[6:7], s[36:37], v[140:141]
	s_mul_i32 s35, s37, 0xba2e8ba3
	s_mul_hi_u32 s38, s36, 0xba2e8ba3
	s_mul_hi_u32 s34, s37, 0xba2e8ba3
	s_add_u32 s35, s35, s38
	s_mul_i32 s31, s36, 0x2e8ba2e8
	s_addc_u32 s34, s34, 0
	s_mul_hi_u32 s30, s36, 0x2e8ba2e8
	s_add_u32 s31, s31, s35
	s_addc_u32 s30, s30, 0
	s_add_u32 s30, s34, s30
	s_addc_u32 s31, 0, 0
	s_mul_i32 s35, s37, 0x2e8ba2e8
	s_mul_hi_u32 s34, s37, 0x2e8ba2e8
	s_add_u32 s30, s35, s30
	s_addc_u32 s31, s34, s31
	s_ashr_i32 s34, s37, 31
	s_mul_i32 s35, s34, 0x2e8ba2e8
	s_mul_hi_u32 s37, s34, 0xba2e8ba3
	s_add_i32 s35, s37, s35
	s_mul_i32 s34, s34, 0xba2e8ba3
	s_add_i32 s35, s35, s34
	s_add_u32 s30, s30, s34
	s_addc_u32 s31, s31, s35
	s_ashr_i64 s[34:35], s[30:31], 10
	s_lshr_b32 s30, s31, 31
	s_add_u32 s30, s34, s30
	s_mulk_i32 s30, 0x1600
	s_sub_i32 s30, s36, s30
	s_sext_i32_i16 s31, s30
	s_bfe_u32 s31, s31, 0x3001c
	s_add_i32 s31, s30, s31
	s_waitcnt vmcnt(8)
	s_waitcnt lgkmcnt(0)
	s_barrier
; #define PG8_STAGE(bufoff, gbase, voff) do { _Pragma("unroll") for (int _i = 0; _i < 2; ++_i) \
;         __builtin_amdgcn_global_load_lds((const unsigned*)((const char*)(gbase) + (voff)[_i]), (LAS unsigned*)(lds + (bufoff) + ldsw + _i * 8192), 16, 0, 0); } while (0)
; #define PG8_LDA(dst, b, h) do { _Pragma("unroll") for (int m = 0; m < 4; ++m) _Pragma("unroll") for (int k = 0; k < 2; ++k) dst[m][k] = *(const LAS bf16x8*)(lds + PG8_SA(b, h) + aoff + m * 2048 + k * 1024); } while (0)
; #define PG8_LDB(dst, b, h) do { _Pragma("unroll") for (int n = 0; n < 2; ++n) _Pragma("unroll") for (int k = 0; k < 2; ++k) dst[n][k] = *(const LAS bf16x8*)(lds + PG8_SB(b, h) + boff + n * 2048 + k * 1024); } while (0)
; #define PG8_MMA(ai, bj, At, Bt) do { __builtin_amdgcn_s_setprio(1); _Pragma("unroll") for (int m = 0; m < 4; ++m) _Pragma("unroll") for (int n = 0; n < 2; ++n) _Pragma("unroll") for (int k = 0; k < 2; ++k) \
;         acc[ai][bj][m][n] = __builtin_amdgcn_mfma_f32_16x16x32_bf16(Bt[n][k], At[m][k], acc[ai][bj][m][n], 0, 0, 0); __builtin_amdgcn_s_setprio(0); } while (0)
; #define PG8_WAIT_V(n) asm volatile("s_waitcnt vmcnt(" #n ")" ::: "memory")
; #define PG8_WAIT_L(n) asm volatile("s_waitcnt lgkmcnt(" #n ")" ::: "memory")
; #define PG8_BAR __builtin_amdgcn_s_barrier()
; #define PG8_SCHED __builtin_amdgcn_sched_barrier(0)
;     DI bool next(int i, Unit& u) const {
;     ...
;         { const int q = nwg / NXCD, r = nwg % NXCD, xcd = wgid % NXCD, off = wgid / NXCD; wgid = (xcd < r ? xcd * (q + 1) : r * (q + 1) + (xcd - r) * q) + off; }
;         const int nig = WGM * nN, gid = wgid / nig, fm = gid * WGM, gsz = (nM - fm) < WGM ? (nM - fm) : WGM;
;         u.pm = fm + ((wgid % nig) % gsz); u.pn = (wgid % nig) / gsz; return true;
; template <class Epi>
; DI void gemm_phase(LAS unsigned char* lds, const int wid, const Gemm g, const Order& S, const Epi& E) {
;     ...
;             PG8_WAIT_V(8); PG8_WAIT_L(0); PG8_BAR; PG8_MMA(1, 0, At, B0); PG8_MMA(1, 1, At, B1); PG8_BAR; PG8_SCHED;
;             PG8_LDB(B0, 1, 0); PG8_LDB(B1, 1, 1); PG8_SCHED; PG8_LDA(At, 1, 0); PG8_STAGE(PG8_SA(0, 1), a2 + hstepA, voffA);
	s_setprio 1
	v_mfma_f32_16x16x32_bf16 v[60:63], v[164:167], v[196:199], 0
	v_mfma_f32_16x16x32_bf16 v[56:59], v[172:175], v[196:199], 0
	v_mfma_f32_16x16x32_bf16 v[44:47], v[164:167], v[204:207], 0
	v_mfma_f32_16x16x32_bf16 v[40:43], v[172:175], v[204:207], 0
	v_mfma_f32_16x16x32_bf16 v[28:31], v[164:167], v[216:219], 0
	v_mfma_f32_16x16x32_bf16 v[24:27], v[172:175], v[216:219], 0
	v_mfma_f32_16x16x32_bf16 v[12:15], v[164:167], v[224:227], 0
	v_mfma_f32_16x16x32_bf16 v[8:11], v[172:175], v[224:227], 0
	v_mfma_f32_16x16x32_bf16 v[60:63], v[168:171], v[200:203], v[60:63]
	v_mfma_f32_16x16x32_bf16 v[56:59], v[176:179], v[200:203], v[56:59]
	v_mfma_f32_16x16x32_bf16 v[44:47], v[168:171], v[208:211], v[44:47]
	v_mfma_f32_16x16x32_bf16 v[40:43], v[176:179], v[208:211], v[40:43]
	v_mfma_f32_16x16x32_bf16 v[28:31], v[168:171], v[220:223], v[28:31]
	v_mfma_f32_16x16x32_bf16 v[24:27], v[176:179], v[220:223], v[24:27]
	v_mfma_f32_16x16x32_bf16 v[12:15], v[168:171], v[228:231], v[12:15]
	v_mfma_f32_16x16x32_bf16 v[8:11], v[176:179], v[228:231], v[8:11]
	v_mfma_f32_16x16x32_bf16 v[52:55], v[180:183], v[196:199], 0
	v_mfma_f32_16x16x32_bf16 v[48:51], v[188:191], v[196:199], 0
	v_mfma_f32_16x16x32_bf16 v[36:39], v[180:183], v[204:207], 0
	v_mfma_f32_16x16x32_bf16 v[32:35], v[188:191], v[204:207], 0
	v_mfma_f32_16x16x32_bf16 v[20:23], v[180:183], v[216:219], 0
	v_mfma_f32_16x16x32_bf16 v[16:19], v[188:191], v[216:219], 0
	v_mfma_f32_16x16x32_bf16 v[4:7], v[180:183], v[224:227], 0
	v_mfma_f32_16x16x32_bf16 v[0:3], v[188:191], v[224:227], 0
	v_mfma_f32_16x16x32_bf16 v[52:55], v[184:187], v[200:203], v[52:55]
	v_mfma_f32_16x16x32_bf16 v[48:51], v[192:195], v[200:203], v[48:51]
	v_mfma_f32_16x16x32_bf16 v[36:39], v[184:187], v[208:211], v[36:39]
	v_mfma_f32_16x16x32_bf16 v[32:35], v[192:195], v[208:211], v[32:35]
	v_mfma_f32_16x16x32_bf16 v[20:23], v[184:187], v[220:223], v[20:23]
	v_mfma_f32_16x16x32_bf16 v[16:19], v[192:195], v[220:223], v[16:19]
	v_mfma_f32_16x16x32_bf16 v[4:7], v[184:187], v[228:231], v[4:7]
	v_mfma_f32_16x16x32_bf16 v[0:3], v[192:195], v[228:231], v[0:3]
	s_setprio 0
	s_barrier
	s_add_i32 s64, 0, 0x18000
	v_add_u32_e32 v146, s64, v147
	s_add_i32 s65, 0, 0x1c000
	ds_read_b128 v[164:167], v146
	ds_read_b128 v[168:171], v146 offset:1024
	ds_read_b128 v[172:175], v146 offset:2048
	ds_read_b128 v[176:179], v146 offset:3072
	v_add_u32_e32 v146, s65, v147
	ds_read_b128 v[180:183], v146
	ds_read_b128 v[184:187], v146 offset:1024
	ds_read_b128 v[188:191], v146 offset:2048
	ds_read_b128 v[192:195], v146 offset:3072
	s_add_u32 s46, s46, 0x40000
	s_addc_u32 s47, s47, 0
	s_mov_b32 m0, s48
	v_lshl_add_u64 v[160:161], s[46:47], 0, v[134:135]
	ds_read_b128 v[196:199], v159 offset:32768
	ds_read_b128 v[200:203], v159 offset:33792
	ds_read_b128 v[204:207], v159 offset:34816
	ds_read_b128 v[208:211], v159 offset:35840
	ds_read_b128 v[216:219], v159 offset:36864
	ds_read_b128 v[220:223], v159 offset:37888
	ds_read_b128 v[224:227], v159 offset:38912
	ds_read_b128 v[228:231], v159 offset:39936
	global_load_lds_dwordx4 v[160:161], off
	v_lshl_add_u64 v[160:161], s[46:47], 0, v[130:131]
	s_mov_b32 m0, s49
	s_nop 0
	global_load_lds_dwordx4 v[160:161], off
	s_sext_i32_i16 s34, s31
	s_and_b32 s31, s31, 0xfff8
	s_sub_i32 s30, s30, s31
	s_ashr_i32 s34, s34, 3
	s_sext_i32_i16 s31, s30
	s_cmp_lt_i32 s31, 0
	s_cselect_b32 s31, s26, 0x2c0
	s_mul_i32 s30, s30, s31
	s_add_i32 s30, s30, s34
	s_sext_i32_i16 s31, s30
	s_mulk_i32 s31, 0xba3
	s_lshr_b32 s34, s31, 31
	s_ashr_i32 s31, s31, 19
	s_add_i32 s31, s31, s34
	s_lshl_b32 s34, s31, 3
	s_mulk_i32 s31, 0xb0
	s_sub_i32 s30, s30, s31
	s_sext_i32_i16 s31, s30
	s_bfe_u32 s31, s31, 0x3001c
	s_add_i32 s31, s30, s31
	s_sext_i32_i16 s35, s31
	s_and_b32 s31, s31, 0xfff8
	s_sub_i32 s30, s30, s31
	s_sext_i32_i16 s30, s30
	s_add_i32 s30, s34, s30
	s_ashr_i32 s34, s35, 3
	s_ashr_i32 s31, s30, 31
	s_lshl_b64 s[36:37], s[30:31], 19
	s_add_u32 s36, s21, s36
	s_addc_u32 s37, s25, s37
	s_and_b64 s[38:39], s[6:7], exec
	s_cselect_b32 s31, s37, s43
	s_cselect_b32 s59, s36, s42
	s_ashr_i32 s35, s34, 31
	s_lshl_b64 s[38:39], s[34:35], 19
	s_add_u32 s38, s8, s38
	s_addc_u32 s39, s9, s39
	s_and_b64 vcc, s[6:7], exec
	s_cselect_b32 s35, s39, s45
	s_cselect_b32 s60, s38, s44
	s_waitcnt vmcnt(8)
	s_waitcnt lgkmcnt(0)
	s_barrier
; #define PG8_STAGE(bufoff, gbase, voff) do { _Pragma("unroll") for (int _i = 0; _i < 2; ++_i) \
;         __builtin_amdgcn_global_load_lds((const unsigned*)((const char*)(gbase) + (voff)[_i]), (LAS unsigned*)(lds + (bufoff) + ldsw + _i * 8192), 16, 0, 0); } while (0)
; #define PG8_LDA(dst, b, h) do { _Pragma("unroll") for (int m = 0; m < 4; ++m) _Pragma("unroll") for (int k = 0; k < 2; ++k) dst[m][k] = *(const LAS bf16x8*)(lds + PG8_SA(b, h) + aoff + m * 2048 + k * 1024); } while (0)
; #define PG8_MMA(ai, bj, At, Bt) do { __builtin_amdgcn_s_setprio(1); _Pragma("unroll") for (int m = 0; m < 4; ++m) _Pragma("unroll") for (int n = 0; n < 2; ++n) _Pragma("unroll") for (int k = 0; k < 2; ++k) \
;         acc[ai][bj][m][n] = __builtin_amdgcn_mfma_f32_16x16x32_bf16(Bt[n][k], At[m][k], acc[ai][bj][m][n], 0, 0, 0); __builtin_amdgcn_s_setprio(0); } while (0)
; #define PG8_WAIT_V(n) asm volatile("s_waitcnt vmcnt(" #n ")" ::: "memory")
; #define PG8_WAIT_L(n) asm volatile("s_waitcnt lgkmcnt(" #n ")" ::: "memory")
; #define PG8_BAR __builtin_amdgcn_s_barrier()
; #define PG8_SCHED __builtin_amdgcn_sched_barrier(0)
; template <class Epi>
; DI void gemm_phase(LAS unsigned char* lds, const int wid, const Gemm g, const Order& S, const Epi& E) {
;     ...
;             PG8_WAIT_V(8); PG8_WAIT_L(0); PG8_BAR; PG8_MMA(0, 0, At, B0); PG8_MMA(0, 1, At, B1); PG8_BAR; PG8_SCHED;
;             PG8_LDA(At, 1, 1); PG8_STAGE(PG8_SB(1, 0), b3, voffB); PG8_STAGE(PG8_SB(1, 1), b3 + hstepB, voffB); PG8_STAGE(PG8_SA(1, 0), a3, voffA);
;             PG8_WAIT_V(8); PG8_WAIT_L(0); PG8_BAR; PG8_MMA(1, 0, At, B0); PG8_MMA(1, 1, At, B1); PG8_BAR; PG8_SCHED;
;         }
	s_setprio 1
	v_mfma_f32_16x16x32_bf16 v[124:127], v[164:167], v[196:199], v[124:127]
	v_mfma_f32_16x16x32_bf16 v[120:123], v[172:175], v[196:199], v[120:123]
	v_mfma_f32_16x16x32_bf16 v[108:111], v[164:167], v[204:207], v[108:111]
	v_mfma_f32_16x16x32_bf16 v[104:107], v[172:175], v[204:207], v[104:107]
	v_mfma_f32_16x16x32_bf16 v[92:95], v[164:167], v[216:219], v[92:95]
	v_mfma_f32_16x16x32_bf16 v[88:91], v[172:175], v[216:219], v[88:91]
	v_mfma_f32_16x16x32_bf16 v[76:79], v[164:167], v[224:227], v[76:79]
	v_mfma_f32_16x16x32_bf16 v[72:75], v[172:175], v[224:227], v[72:75]
	v_mfma_f32_16x16x32_bf16 v[124:127], v[168:171], v[200:203], v[124:127]
	v_mfma_f32_16x16x32_bf16 v[120:123], v[176:179], v[200:203], v[120:123]
	v_mfma_f32_16x16x32_bf16 v[108:111], v[168:171], v[208:211], v[108:111]
	v_mfma_f32_16x16x32_bf16 v[104:107], v[176:179], v[208:211], v[104:107]
	v_mfma_f32_16x16x32_bf16 v[92:95], v[168:171], v[220:223], v[92:95]
	v_mfma_f32_16x16x32_bf16 v[88:91], v[176:179], v[220:223], v[88:91]
	v_mfma_f32_16x16x32_bf16 v[76:79], v[168:171], v[228:231], v[76:79]
	v_mfma_f32_16x16x32_bf16 v[72:75], v[176:179], v[228:231], v[72:75]
	v_mfma_f32_16x16x32_bf16 v[116:119], v[180:183], v[196:199], v[116:119]
	v_mfma_f32_16x16x32_bf16 v[112:115], v[188:191], v[196:199], v[112:115]
	v_mfma_f32_16x16x32_bf16 v[100:103], v[180:183], v[204:207], v[100:103]
	v_mfma_f32_16x16x32_bf16 v[96:99], v[188:191], v[204:207], v[96:99]
	v_mfma_f32_16x16x32_bf16 v[84:87], v[180:183], v[216:219], v[84:87]
	v_mfma_f32_16x16x32_bf16 v[80:83], v[188:191], v[216:219], v[80:83]
	v_mfma_f32_16x16x32_bf16 v[68:71], v[180:183], v[224:227], v[68:71]
	v_mfma_f32_16x16x32_bf16 v[64:67], v[188:191], v[224:227], v[64:67]
	v_mfma_f32_16x16x32_bf16 v[116:119], v[184:187], v[200:203], v[116:119]
	v_mfma_f32_16x16x32_bf16 v[112:115], v[192:195], v[200:203], v[112:115]
	v_mfma_f32_16x16x32_bf16 v[100:103], v[184:187], v[208:211], v[100:103]
	v_mfma_f32_16x16x32_bf16 v[96:99], v[192:195], v[208:211], v[96:99]
	v_mfma_f32_16x16x32_bf16 v[84:87], v[184:187], v[220:223], v[84:87]
	v_mfma_f32_16x16x32_bf16 v[80:83], v[192:195], v[220:223], v[80:83]
	v_mfma_f32_16x16x32_bf16 v[68:71], v[184:187], v[228:231], v[68:71]
	v_mfma_f32_16x16x32_bf16 v[64:67], v[192:195], v[228:231], v[64:67]
	s_setprio 0
	s_barrier
	s_add_i32 s46, s64, s94
	v_lshl_add_u64 v[144:145], v[144:145], 0, s[16:17]
	s_mov_b32 m0, s46
	ds_read_b128 v[196:199], v159 offset:49152
	ds_read_b128 v[200:203], v159 offset:50176
	ds_read_b128 v[204:207], v159 offset:51200
	ds_read_b128 v[208:211], v159 offset:52224
	ds_read_b128 v[216:219], v159 offset:53248
	ds_read_b128 v[220:223], v159 offset:54272
	ds_read_b128 v[224:227], v159 offset:55296
	ds_read_b128 v[228:231], v159 offset:56320
	global_load_lds_dwordx4 v[144:145], off
	s_add_i32 m0, s46, 0x2000
	s_add_u32 s44, s44, 0x40080
	v_lshl_add_u64 v[144:145], v[148:149], 0, s[16:17]
	s_addc_u32 s45, s45, 0
	s_add_i32 s46, s65, s94
	global_load_lds_dwordx4 v[144:145], off
	v_lshl_add_u64 v[144:145], s[44:45], 0, v[132:133]
	s_mov_b32 m0, s46
	s_nop 0
	global_load_lds_dwordx4 v[144:145], off
	v_lshl_add_u64 v[144:145], s[44:45], 0, v[128:129]
	s_add_i32 m0, s46, 0x2000
	s_nop 0
	global_load_lds_dwordx4 v[144:145], off
	v_lshl_add_u64 v[144:145], v[152:153], 0, s[16:17]
	s_mov_b32 m0, s51
	s_nop 0
	global_load_lds_dwordx4 v[144:145], off
	v_lshl_add_u64 v[144:145], v[156:157], 0, s[16:17]
	s_mov_b32 m0, s52
	s_nop 0
	global_load_lds_dwordx4 v[144:145], off
	s_waitcnt vmcnt(8)
	s_waitcnt lgkmcnt(0)
	s_barrier
	s_setprio 1
	v_mfma_f32_16x16x32_bf16 v[60:63], v[164:167], v[196:199], v[60:63]
	v_mfma_f32_16x16x32_bf16 v[56:59], v[172:175], v[196:199], v[56:59]
	v_mfma_f32_16x16x32_bf16 v[44:47], v[164:167], v[204:207], v[44:47]
	v_mfma_f32_16x16x32_bf16 v[40:43], v[172:175], v[204:207], v[40:43]
	v_mfma_f32_16x16x32_bf16 v[28:31], v[164:167], v[216:219], v[28:31]
	v_mfma_f32_16x16x32_bf16 v[24:27], v[172:175], v[216:219], v[24:27]
	v_mfma_f32_16x16x32_bf16 v[12:15], v[164:167], v[224:227], v[12:15]
	v_mfma_f32_16x16x32_bf16 v[8:11], v[172:175], v[224:227], v[8:11]
	v_mfma_f32_16x16x32_bf16 v[60:63], v[168:171], v[200:203], v[60:63]
	v_mfma_f32_16x16x32_bf16 v[56:59], v[176:179], v[200:203], v[56:59]
	v_mfma_f32_16x16x32_bf16 v[44:47], v[168:171], v[208:211], v[44:47]
	v_mfma_f32_16x16x32_bf16 v[40:43], v[176:179], v[208:211], v[40:43]
	v_mfma_f32_16x16x32_bf16 v[28:31], v[168:171], v[220:223], v[28:31]
	v_mfma_f32_16x16x32_bf16 v[24:27], v[176:179], v[220:223], v[24:27]
	v_mfma_f32_16x16x32_bf16 v[12:15], v[168:171], v[228:231], v[12:15]
	v_mfma_f32_16x16x32_bf16 v[8:11], v[176:179], v[228:231], v[8:11]
	v_mfma_f32_16x16x32_bf16 v[52:55], v[180:183], v[196:199], v[52:55]
	v_mfma_f32_16x16x32_bf16 v[48:51], v[188:191], v[196:199], v[48:51]
	v_mfma_f32_16x16x32_bf16 v[36:39], v[180:183], v[204:207], v[36:39]
	v_mfma_f32_16x16x32_bf16 v[32:35], v[188:191], v[204:207], v[32:35]
	v_mfma_f32_16x16x32_bf16 v[20:23], v[180:183], v[216:219], v[20:23]
	v_mfma_f32_16x16x32_bf16 v[16:19], v[188:191], v[216:219], v[16:19]
	v_mfma_f32_16x16x32_bf16 v[4:7], v[180:183], v[224:227], v[4:7]
	v_mfma_f32_16x16x32_bf16 v[0:3], v[188:191], v[224:227], v[0:3]
	v_mfma_f32_16x16x32_bf16 v[52:55], v[184:187], v[200:203], v[52:55]
	v_mfma_f32_16x16x32_bf16 v[48:51], v[192:195], v[200:203], v[48:51]
	v_mfma_f32_16x16x32_bf16 v[36:39], v[184:187], v[208:211], v[36:39]
	v_mfma_f32_16x16x32_bf16 v[32:35], v[192:195], v[208:211], v[32:35]
	v_mfma_f32_16x16x32_bf16 v[20:23], v[184:187], v[220:223], v[20:23]
	v_mfma_f32_16x16x32_bf16 v[16:19], v[192:195], v[220:223], v[16:19]
	v_mfma_f32_16x16x32_bf16 v[4:7], v[184:187], v[228:231], v[4:7]
	v_mfma_f32_16x16x32_bf16 v[0:3], v[192:195], v[228:231], v[0:3]
	s_setprio 0
	s_barrier
	s_add_i32 s63, s63, 2
	s_add_u32 s42, s42, 0x100
	s_addc_u32 s43, s43, 0
	s_add_u32 s61, s61, 0x100
	s_addc_u32 s62, s62, 0
	s_cmp_gt_u32 s63, 13
	s_cbranch_scc0 .LBB0_228
	s_branch .Lpeel_exit_0

; #define PG8_STAGE(bufoff, gbase, voff) do { _Pragma("unroll") for (int _i = 0; _i < 2; ++_i) \
;         __builtin_amdgcn_global_load_lds((const unsigned*)((const char*)(gbase) + (voff)[_i]), (LAS unsigned*)(lds + (bufoff) + ldsw + _i * 8192), 16, 0, 0); } while (0)
; #define PG8_LDA(dst, b, h) do { _Pragma("unroll") for (int m = 0; m < 4; ++m) _Pragma("unroll") for (int k = 0; k < 2; ++k) dst[m][k] = *(const LAS bf16x8*)(lds + PG8_SA(b, h) + aoff + m * 2048 + k * 1024); } while (0)
; #define PG8_LDB(dst, b, h) do { _Pragma("unroll") for (int n = 0; n < 2; ++n) _Pragma("unroll") for (int k = 0; k < 2; ++k) dst[n][k] = *(const LAS bf16x8*)(lds + PG8_SB(b, h) + boff + n * 2048 + k * 1024); } while (0)
; #define PG8_MMA(ai, bj, At, Bt) do { __builtin_amdgcn_s_setprio(1); _Pragma("unroll") for (int m = 0; m < 4; ++m) _Pragma("unroll") for (int n = 0; n < 2; ++n) _Pragma("unroll") for (int k = 0; k < 2; ++k) \
;         acc[ai][bj][m][n] = __builtin_amdgcn_mfma_f32_16x16x32_bf16(Bt[n][k], At[m][k], acc[ai][bj][m][n], 0, 0, 0); __builtin_amdgcn_s_setprio(0); } while (0)
; #define PG8_WAIT_V(n) asm volatile("s_waitcnt vmcnt(" #n ")" ::: "memory")
; #define PG8_WAIT_L(n) asm volatile("s_waitcnt lgkmcnt(" #n ")" ::: "memory")
; #define PG8_BAR __builtin_amdgcn_s_barrier()
; #define PG8_SCHED __builtin_amdgcn_sched_barrier(0)
;     DI bool next(int i, Unit& u) const {
;         const long L = (long)i * G + c; if (L >= total) return false;
;         u.g = (int)(L / nwg); int wgid = (int)(L % nwg);
;         { const int q = nwg / NXCD, r = nwg % NXCD, xcd = wgid % NXCD, off = wgid / NXCD; wgid = (xcd < r ? xcd * (q + 1) : r * (q + 1) + (xcd - r) * q) + off; }
; template <class Epi>
; DI void gemm_phase(LAS unsigned char* lds, const int wid, const Gemm g, const Order& S, const Epi& E) {
;     ...
;             PG8_LDB(B0, 0, 0); PG8_LDB(B1, 0, 1); PG8_SCHED; PG8_LDA(At, 0, 0); PG8_STAGE(PG8_SA(1, 1), a1 + hstepA, voffA);
;             PG8_WAIT_V(8); PG8_WAIT_L(0); PG8_BAR; PG8_MMA(0, 0, At, B0); PG8_MMA(0, 1, At, B1); PG8_BAR; PG8_SCHED;
;             PG8_LDA(At, 0, 1); PG8_STAGE(PG8_SB(0, 0), b2, voffB); PG8_STAGE(PG8_SB(0, 1), b2 + hstepB, voffB); PG8_STAGE(PG8_SA(0, 0), a2, voffA);
.LBB0_397:
.LBB0_399:
	s_add_u32 s12, s12, 0x40080
	s_addc_u32 s13, s13, 0
	s_add_u32 s68, s64, 0x100
	v_mov_b32_e32 v0, 0
	s_addc_u32 s69, s65, 0
	s_mov_b32 s70, -2
	s_waitcnt lgkmcnt(0)
	ds_read_b128 v[146:149], v163
	ds_read_b128 v[150:153], v163 offset:1024
	ds_read_b128 v[154:157], v163 offset:2048
	ds_read_b128 v[158:161], v163 offset:3072
	ds_read_b128 v[168:171], v164
	ds_read_b128 v[172:175], v164 offset:1024
	ds_read_b128 v[176:179], v164 offset:2048
	ds_read_b128 v[180:183], v164 offset:3072
	s_add_u32 s64, s12, 0xfffc0080
	s_addc_u32 s65, s13, -1
	s_cmp_eq_u32 s70, 12
	s_cselect_b32 s67, s11, s65
	s_cselect_b32 s66, s16, s64
	s_cselect_b32 s65, s57, s69
	s_cselect_b32 s64, s59, s68
	v_lshl_add_u64 v[212:213], s[12:13], 0, v[138:139]
	s_add_i32 m0, s6, 0xc000
	ds_read_b128 v[184:187], v165
	ds_read_b128 v[188:191], v165 offset:1024
	ds_read_b128 v[192:195], v165 offset:2048
	ds_read_b128 v[196:199], v165 offset:3072
	ds_read_b128 v[200:203], v165 offset:4096
	ds_read_b128 v[204:207], v165 offset:5120
	ds_read_b128 v[208:211], v165 offset:6144
	ds_read_b128 v[216:219], v165 offset:7168
	global_load_lds_dwordx4 v[212:213], off
	v_lshl_add_u64 v[212:213], s[12:13], 0, v[140:141]
	s_add_i32 m0, s6, 0xe000
	s_nop 0
	global_load_lds_dwordx4 v[212:213], off
	s_waitcnt vmcnt(8)
	s_waitcnt lgkmcnt(0)
	s_barrier
	s_setprio 1
	v_mfma_f32_16x16x32_bf16 v[124:127], v[146:149], v[184:187], 0
	v_mfma_f32_16x16x32_bf16 v[120:123], v[154:157], v[184:187], 0
	v_mfma_f32_16x16x32_bf16 v[108:111], v[146:149], v[192:195], 0
	v_mfma_f32_16x16x32_bf16 v[104:107], v[154:157], v[192:195], 0
	v_mfma_f32_16x16x32_bf16 v[92:95], v[146:149], v[200:203], 0
	v_mfma_f32_16x16x32_bf16 v[88:91], v[154:157], v[200:203], 0
	v_mfma_f32_16x16x32_bf16 v[76:79], v[146:149], v[208:211], 0
	v_mfma_f32_16x16x32_bf16 v[72:75], v[154:157], v[208:211], 0
	v_mfma_f32_16x16x32_bf16 v[124:127], v[150:153], v[188:191], v[124:127]
	v_mfma_f32_16x16x32_bf16 v[120:123], v[158:161], v[188:191], v[120:123]
	v_mfma_f32_16x16x32_bf16 v[108:111], v[150:153], v[196:199], v[108:111]
	v_mfma_f32_16x16x32_bf16 v[104:107], v[158:161], v[196:199], v[104:107]
	v_mfma_f32_16x16x32_bf16 v[92:95], v[150:153], v[204:207], v[92:95]
	v_mfma_f32_16x16x32_bf16 v[88:91], v[158:161], v[204:207], v[88:91]
	v_mfma_f32_16x16x32_bf16 v[76:79], v[150:153], v[216:219], v[76:79]
	v_mfma_f32_16x16x32_bf16 v[72:75], v[158:161], v[216:219], v[72:75]
	v_mfma_f32_16x16x32_bf16 v[116:119], v[168:171], v[184:187], 0
	v_mfma_f32_16x16x32_bf16 v[112:115], v[176:179], v[184:187], 0
	v_mfma_f32_16x16x32_bf16 v[100:103], v[168:171], v[192:195], 0
	v_mfma_f32_16x16x32_bf16 v[96:99], v[176:179], v[192:195], 0
	v_mfma_f32_16x16x32_bf16 v[84:87], v[168:171], v[200:203], 0
	v_mfma_f32_16x16x32_bf16 v[80:83], v[176:179], v[200:203], 0
	v_mfma_f32_16x16x32_bf16 v[68:71], v[168:171], v[208:211], 0
	v_mfma_f32_16x16x32_bf16 v[64:67], v[176:179], v[208:211], 0
	v_mfma_f32_16x16x32_bf16 v[116:119], v[172:175], v[188:191], v[116:119]
	v_mfma_f32_16x16x32_bf16 v[112:115], v[180:183], v[188:191], v[112:115]
	v_mfma_f32_16x16x32_bf16 v[100:103], v[172:175], v[196:199], v[100:103]
	v_mfma_f32_16x16x32_bf16 v[96:99], v[180:183], v[196:199], v[96:99]
	v_mfma_f32_16x16x32_bf16 v[84:87], v[172:175], v[204:207], v[84:87]
	v_mfma_f32_16x16x32_bf16 v[80:83], v[180:183], v[204:207], v[80:83]
	v_mfma_f32_16x16x32_bf16 v[68:71], v[172:175], v[216:219], v[68:71]
	v_mfma_f32_16x16x32_bf16 v[64:67], v[180:183], v[216:219], v[64:67]
	s_setprio 0
	s_barrier
	s_add_i32 s71, s82, s94
	v_lshl_add_u64 v[212:213], s[64:65], 0, v[130:131]
	s_mov_b32 m0, s71
	ds_read_b128 v[184:187], v165 offset:16384
	ds_read_b128 v[188:191], v165 offset:17408
	ds_read_b128 v[192:195], v165 offset:18432
	ds_read_b128 v[196:199], v165 offset:19456
	ds_read_b128 v[200:203], v165 offset:20480
	ds_read_b128 v[204:207], v165 offset:21504
	ds_read_b128 v[208:211], v165 offset:22528
	ds_read_b128 v[216:219], v165 offset:23552
	global_load_lds_dwordx4 v[212:213], off
	s_add_i32 m0, s71, 0x2000
	s_add_u32 s86, s64, 0x40000
	v_lshl_add_u64 v[214:215], s[64:65], 0, v[134:135]
	s_addc_u32 s87, s65, 0
	s_add_i32 s71, s83, s94
	global_load_lds_dwordx4 v[214:215], off
	v_lshl_add_u64 v[220:221], s[86:87], 0, v[130:131]
	s_mov_b32 m0, s71
	v_lshl_add_u64 v[222:223], s[66:67], 0, v[132:133]
	global_load_lds_dwordx4 v[220:221], off
	v_lshl_add_u64 v[220:221], s[86:87], 0, v[134:135]
	s_add_i32 m0, s71, 0x2000
	s_nop 0
	global_load_lds_dwordx4 v[220:221], off
	v_lshl_add_u64 v[220:221], s[66:67], 0, v[128:129]
	s_mov_b32 m0, s6
	s_nop 0
	global_load_lds_dwordx4 v[220:221], off
	s_mov_b32 m0, s7
	s_nop 0
	global_load_lds_dwordx4 v[222:223], off
	s_add_i32 s85, s85, 1
	s_mul_i32 s8, s85, s78
	s_mul_hi_u32 s9, s85, s79
	s_add_i32 s9, s9, s8
	s_mul_i32 s8, s85, s79
	s_add_u32 s60, s8, s2
	s_addc_u32 s61, s9, s3
	v_cmp_lt_i64_e64 s[8:9], s[60:61], v[142:143]
	s_mul_i32 s57, s61, 0xaaaaaaab
	s_mul_hi_u32 s58, s60, 0xaaaaaaab
	s_mul_hi_u32 s56, s61, 0xaaaaaaab
	s_add_u32 s57, s57, s58
	s_mul_i32 s16, s60, 0x2aaaaaaa
	s_addc_u32 s56, s56, 0
	s_mul_hi_u32 s11, s60, 0x2aaaaaaa
	s_add_u32 s16, s16, s57
	s_addc_u32 s11, s11, 0
	s_add_u32 s11, s56, s11
	s_addc_u32 s16, 0, 0
	s_mul_i32 s57, s61, 0x2aaaaaaa
	s_mul_hi_u32 s56, s61, 0x2aaaaaaa
	s_add_u32 s11, s57, s11
	s_addc_u32 s16, s56, s16
	s_ashr_i32 s56, s61, 31
	s_mul_i32 s57, s56, 0x2aaaaaaa
	s_mul_hi_u32 s58, s56, 0xaaaaaaab
	s_add_i32 s57, s58, s57
	s_mul_i32 s56, s56, 0xaaaaaaab
	s_add_i32 s57, s57, s56
	s_add_u32 s56, s11, s56
	s_addc_u32 s57, s16, s57
	s_ashr_i64 s[58:59], s[56:57], 9
	s_lshr_b32 s11, s57, 31
	s_add_u32 s11, s58, s11
	s_mulk_i32 s11, 0xc00
	s_sub_i32 s11, s60, s11
	s_sext_i32_i16 s16, s11
	s_bfe_u32 s16, s16, 0x3001c
	s_add_i32 s16, s11, s16
	s_sext_i32_i16 s56, s16
	s_waitcnt vmcnt(8)
	s_waitcnt lgkmcnt(0)
	s_barrier
; #define PG8_STAGE(bufoff, gbase, voff) do { _Pragma("unroll") for (int _i = 0; _i < 2; ++_i) \
;         __builtin_amdgcn_global_load_lds((const unsigned*)((const char*)(gbase) + (voff)[_i]), (LAS unsigned*)(lds + (bufoff) + ldsw + _i * 8192), 16, 0, 0); } while (0)
; #define PG8_LDA(dst, b, h) do { _Pragma("unroll") for (int m = 0; m < 4; ++m) _Pragma("unroll") for (int k = 0; k < 2; ++k) dst[m][k] = *(const LAS bf16x8*)(lds + PG8_SA(b, h) + aoff + m * 2048 + k * 1024); } while (0)
; #define PG8_LDB(dst, b, h) do { _Pragma("unroll") for (int n = 0; n < 2; ++n) _Pragma("unroll") for (int k = 0; k < 2; ++k) dst[n][k] = *(const LAS bf16x8*)(lds + PG8_SB(b, h) + boff + n * 2048 + k * 1024); } while (0)
; #define PG8_MMA(ai, bj, At, Bt) do { __builtin_amdgcn_s_setprio(1); _Pragma("unroll") for (int m = 0; m < 4; ++m) _Pragma("unroll") for (int n = 0; n < 2; ++n) _Pragma("unroll") for (int k = 0; k < 2; ++k) \
;         acc[ai][bj][m][n] = __builtin_amdgcn_mfma_f32_16x16x32_bf16(Bt[n][k], At[m][k], acc[ai][bj][m][n], 0, 0, 0); __builtin_amdgcn_s_setprio(0); } while (0)
; #define PG8_WAIT_V(n) asm volatile("s_waitcnt vmcnt(" #n ")" ::: "memory")
; #define PG8_WAIT_L(n) asm volatile("s_waitcnt lgkmcnt(" #n ")" ::: "memory")
; #define PG8_BAR __builtin_amdgcn_s_barrier()
; #define PG8_SCHED __builtin_amdgcn_sched_barrier(0)
;     DI bool next(int i, Unit& u) const {
;     ...
;         { const int q = nwg / NXCD, r = nwg % NXCD, xcd = wgid % NXCD, off = wgid / NXCD; wgid = (xcd < r ? xcd * (q + 1) : r * (q + 1) + (xcd - r) * q) + off; }
;         const int nig = WGM * nN, gid = wgid / nig, fm = gid * WGM, gsz = (nM - fm) < WGM ? (nM - fm) : WGM;
;         u.pm = fm + ((wgid % nig) % gsz); u.pn = (wgid % nig) / gsz; return true;
; template <class Epi>
; DI void gemm_phase(LAS unsigned char* lds, const int wid, const Gemm g, const Order& S, const Epi& E) {
;     ...
;             PG8_WAIT_V(8); PG8_WAIT_L(0); PG8_BAR; PG8_MMA(1, 0, At, B0); PG8_MMA(1, 1, At, B1); PG8_BAR; PG8_SCHED;
;             PG8_LDB(B0, 1, 0); PG8_LDB(B1, 1, 1); PG8_SCHED; PG8_LDA(At, 1, 0); PG8_STAGE(PG8_SA(0, 1), a2 + hstepA, voffA);
	s_setprio 1
	v_mfma_f32_16x16x32_bf16 v[60:63], v[146:149], v[184:187], 0
	v_mfma_f32_16x16x32_bf16 v[56:59], v[154:157], v[184:187], 0
	v_mfma_f32_16x16x32_bf16 v[44:47], v[146:149], v[192:195], 0
	v_mfma_f32_16x16x32_bf16 v[40:43], v[154:157], v[192:195], 0
	v_mfma_f32_16x16x32_bf16 v[28:31], v[146:149], v[200:203], 0
	v_mfma_f32_16x16x32_bf16 v[24:27], v[154:157], v[200:203], 0
	v_mfma_f32_16x16x32_bf16 v[12:15], v[146:149], v[208:211], 0
	v_mfma_f32_16x16x32_bf16 v[8:11], v[154:157], v[208:211], 0
	v_mfma_f32_16x16x32_bf16 v[60:63], v[150:153], v[188:191], v[60:63]
	v_mfma_f32_16x16x32_bf16 v[56:59], v[158:161], v[188:191], v[56:59]
	v_mfma_f32_16x16x32_bf16 v[44:47], v[150:153], v[196:199], v[44:47]
	v_mfma_f32_16x16x32_bf16 v[40:43], v[158:161], v[196:199], v[40:43]
	v_mfma_f32_16x16x32_bf16 v[28:31], v[150:153], v[204:207], v[28:31]
	v_mfma_f32_16x16x32_bf16 v[24:27], v[158:161], v[204:207], v[24:27]
	v_mfma_f32_16x16x32_bf16 v[12:15], v[150:153], v[216:219], v[12:15]
	v_mfma_f32_16x16x32_bf16 v[8:11], v[158:161], v[216:219], v[8:11]
	v_mfma_f32_16x16x32_bf16 v[52:55], v[168:171], v[184:187], 0
	v_mfma_f32_16x16x32_bf16 v[48:51], v[176:179], v[184:187], 0
	v_mfma_f32_16x16x32_bf16 v[36:39], v[168:171], v[192:195], 0
	v_mfma_f32_16x16x32_bf16 v[32:35], v[176:179], v[192:195], 0
	v_mfma_f32_16x16x32_bf16 v[20:23], v[168:171], v[200:203], 0
	v_mfma_f32_16x16x32_bf16 v[16:19], v[176:179], v[200:203], 0
	v_mfma_f32_16x16x32_bf16 v[4:7], v[168:171], v[208:211], 0
	v_mfma_f32_16x16x32_bf16 v[0:3], v[176:179], v[208:211], 0
	v_mfma_f32_16x16x32_bf16 v[52:55], v[172:175], v[188:191], v[52:55]
	v_mfma_f32_16x16x32_bf16 v[48:51], v[180:183], v[188:191], v[48:51]
	v_mfma_f32_16x16x32_bf16 v[36:39], v[172:175], v[196:199], v[36:39]
	v_mfma_f32_16x16x32_bf16 v[32:35], v[180:183], v[196:199], v[32:35]
	v_mfma_f32_16x16x32_bf16 v[20:23], v[172:175], v[204:207], v[20:23]
	v_mfma_f32_16x16x32_bf16 v[16:19], v[180:183], v[204:207], v[16:19]
	v_mfma_f32_16x16x32_bf16 v[4:7], v[172:175], v[216:219], v[4:7]
	v_mfma_f32_16x16x32_bf16 v[0:3], v[180:183], v[216:219], v[0:3]
	s_setprio 0
	s_barrier
	s_add_i32 s71, 0, 0x18000
	v_add_u32_e32 v136, s71, v162
	s_add_i32 s86, 0, 0x1c000
	ds_read_b128 v[146:149], v136
	ds_read_b128 v[150:153], v136 offset:1024
	ds_read_b128 v[154:157], v136 offset:2048
	ds_read_b128 v[158:161], v136 offset:3072
	v_add_u32_e32 v136, s86, v162
	ds_read_b128 v[168:171], v136
	ds_read_b128 v[172:175], v136 offset:1024
	ds_read_b128 v[176:179], v136 offset:2048
	ds_read_b128 v[180:183], v136 offset:3072
	s_add_u32 s66, s66, 0x40000
	s_addc_u32 s67, s67, 0
	s_mov_b32 m0, s21
	v_lshl_add_u64 v[224:225], s[66:67], 0, v[128:129]
	ds_read_b128 v[184:187], v165 offset:32768
	ds_read_b128 v[188:191], v165 offset:33792
	ds_read_b128 v[192:195], v165 offset:34816
	ds_read_b128 v[196:199], v165 offset:35840
	ds_read_b128 v[200:203], v165 offset:36864
	ds_read_b128 v[204:207], v165 offset:37888
	ds_read_b128 v[208:211], v165 offset:38912
	ds_read_b128 v[216:219], v165 offset:39936
	global_load_lds_dwordx4 v[224:225], off
	v_lshl_add_u64 v[224:225], s[66:67], 0, v[132:133]
	s_mov_b32 m0, s26
	s_nop 0
	global_load_lds_dwordx4 v[224:225], off
	s_and_b32 s16, s16, 0xfff8
	s_sub_i32 s11, s11, s16
	s_ashr_i32 s56, s56, 3
	s_sext_i32_i16 s16, s11
	s_cmp_lt_i32 s16, 0
	s_movk_i32 s16, 0x181
	s_cselect_b32 s16, s16, 0x180
	s_mul_i32 s11, s11, s16
	s_add_i32 s11, s11, s56
	s_sext_i32_i16 s16, s11
	s_mulk_i32 s16, 0x2aab
	s_lshr_b32 s56, s16, 31
	s_ashr_i32 s16, s16, 20
	s_add_i32 s16, s16, s56
	s_lshl_b32 s56, s16, 3
	s_mulk_i32 s16, 0x60
	s_sub_i32 s11, s11, s16
	s_bfe_i32 s16, s11, 0x80000
	s_bfe_u32 s16, s16, 0x3000c
	s_add_i32 s16, s11, s16
	s_bfe_i32 s57, s16, 0x80000
	s_and_b32 s16, s16, 0xf8
	s_sub_i32 s11, s11, s16
	s_sext_i32_i16 s57, s57
	s_sext_i32_i8 s11, s11
	s_add_i32 s56, s56, s11
	s_ashr_i32 s58, s57, 3
	s_ashr_i32 s57, s56, 31
	s_lshl_b64 s[60:61], s[56:57], 19
	s_add_u32 s60, s73, s60
	s_addc_u32 s61, s74, s61
	s_and_b64 s[62:63], s[8:9], exec
	s_cselect_b32 s11, s61, s13
	s_cselect_b32 s16, s60, s12
	s_ashr_i32 s59, s58, 31
	s_lshl_b64 s[62:63], s[58:59], 19
	s_add_u32 s62, s75, s62
	s_addc_u32 s63, s76, s63
	s_and_b64 vcc, s[8:9], exec
	s_cselect_b32 s57, s63, s65
	s_cselect_b32 s59, s62, s64
	s_waitcnt vmcnt(8)
	s_waitcnt lgkmcnt(0)
	s_barrier
; #define PG8_STAGE(bufoff, gbase, voff) do { _Pragma("unroll") for (int _i = 0; _i < 2; ++_i) \
;         __builtin_amdgcn_global_load_lds((const unsigned*)((const char*)(gbase) + (voff)[_i]), (LAS unsigned*)(lds + (bufoff) + ldsw + _i * 8192), 16, 0, 0); } while (0)
; #define PG8_LDA(dst, b, h) do { _Pragma("unroll") for (int m = 0; m < 4; ++m) _Pragma("unroll") for (int k = 0; k < 2; ++k) dst[m][k] = *(const LAS bf16x8*)(lds + PG8_SA(b, h) + aoff + m * 2048 + k * 1024); } while (0)
; #define PG8_MMA(ai, bj, At, Bt) do { __builtin_amdgcn_s_setprio(1); _Pragma("unroll") for (int m = 0; m < 4; ++m) _Pragma("unroll") for (int n = 0; n < 2; ++n) _Pragma("unroll") for (int k = 0; k < 2; ++k) \
;         acc[ai][bj][m][n] = __builtin_amdgcn_mfma_f32_16x16x32_bf16(Bt[n][k], At[m][k], acc[ai][bj][m][n], 0, 0, 0); __builtin_amdgcn_s_setprio(0); } while (0)
; #define PG8_WAIT_V(n) asm volatile("s_waitcnt vmcnt(" #n ")" ::: "memory")
; #define PG8_WAIT_L(n) asm volatile("s_waitcnt lgkmcnt(" #n ")" ::: "memory")
; #define PG8_BAR __builtin_amdgcn_s_barrier()
; #define PG8_SCHED __builtin_amdgcn_sched_barrier(0)
; template <class Epi>
; DI void gemm_phase(LAS unsigned char* lds, const int wid, const Gemm g, const Order& S, const Epi& E) {
;     ...
;             PG8_WAIT_V(8); PG8_WAIT_L(0); PG8_BAR; PG8_MMA(0, 0, At, B0); PG8_MMA(0, 1, At, B1); PG8_BAR; PG8_SCHED;
;             PG8_LDA(At, 1, 1); PG8_STAGE(PG8_SB(1, 0), b3, voffB); PG8_STAGE(PG8_SB(1, 1), b3 + hstepB, voffB); PG8_STAGE(PG8_SA(1, 0), a3, voffA);
;             PG8_WAIT_V(8); PG8_WAIT_L(0); PG8_BAR; PG8_MMA(1, 0, At, B0); PG8_MMA(1, 1, At, B1); PG8_BAR; PG8_SCHED;
;         }
	s_setprio 1
	v_mfma_f32_16x16x32_bf16 v[124:127], v[146:149], v[184:187], v[124:127]
	v_mfma_f32_16x16x32_bf16 v[120:123], v[154:157], v[184:187], v[120:123]
	v_mfma_f32_16x16x32_bf16 v[108:111], v[146:149], v[192:195], v[108:111]
	v_mfma_f32_16x16x32_bf16 v[104:107], v[154:157], v[192:195], v[104:107]
	v_mfma_f32_16x16x32_bf16 v[92:95], v[146:149], v[200:203], v[92:95]
	v_mfma_f32_16x16x32_bf16 v[88:91], v[154:157], v[200:203], v[88:91]
	v_mfma_f32_16x16x32_bf16 v[76:79], v[146:149], v[208:211], v[76:79]
	v_mfma_f32_16x16x32_bf16 v[72:75], v[154:157], v[208:211], v[72:75]
	v_mfma_f32_16x16x32_bf16 v[124:127], v[150:153], v[188:191], v[124:127]
	v_mfma_f32_16x16x32_bf16 v[120:123], v[158:161], v[188:191], v[120:123]
	v_mfma_f32_16x16x32_bf16 v[108:111], v[150:153], v[196:199], v[108:111]
	v_mfma_f32_16x16x32_bf16 v[104:107], v[158:161], v[196:199], v[104:107]
	v_mfma_f32_16x16x32_bf16 v[92:95], v[150:153], v[204:207], v[92:95]
	v_mfma_f32_16x16x32_bf16 v[88:91], v[158:161], v[204:207], v[88:91]
	v_mfma_f32_16x16x32_bf16 v[76:79], v[150:153], v[216:219], v[76:79]
	v_mfma_f32_16x16x32_bf16 v[72:75], v[158:161], v[216:219], v[72:75]
	v_mfma_f32_16x16x32_bf16 v[116:119], v[168:171], v[184:187], v[116:119]
	v_mfma_f32_16x16x32_bf16 v[112:115], v[176:179], v[184:187], v[112:115]
	v_mfma_f32_16x16x32_bf16 v[100:103], v[168:171], v[192:195], v[100:103]
	v_mfma_f32_16x16x32_bf16 v[96:99], v[176:179], v[192:195], v[96:99]
	v_mfma_f32_16x16x32_bf16 v[84:87], v[168:171], v[200:203], v[84:87]
	v_mfma_f32_16x16x32_bf16 v[80:83], v[176:179], v[200:203], v[80:83]
	v_mfma_f32_16x16x32_bf16 v[68:71], v[168:171], v[208:211], v[68:71]
	v_mfma_f32_16x16x32_bf16 v[64:67], v[176:179], v[208:211], v[64:67]
	v_mfma_f32_16x16x32_bf16 v[116:119], v[172:175], v[188:191], v[116:119]
	v_mfma_f32_16x16x32_bf16 v[112:115], v[180:183], v[188:191], v[112:115]
	v_mfma_f32_16x16x32_bf16 v[100:103], v[172:175], v[196:199], v[100:103]
	v_mfma_f32_16x16x32_bf16 v[96:99], v[180:183], v[196:199], v[96:99]
	v_mfma_f32_16x16x32_bf16 v[84:87], v[172:175], v[204:207], v[84:87]
	v_mfma_f32_16x16x32_bf16 v[80:83], v[180:183], v[204:207], v[80:83]
	v_mfma_f32_16x16x32_bf16 v[68:71], v[172:175], v[216:219], v[68:71]
	v_mfma_f32_16x16x32_bf16 v[64:67], v[180:183], v[216:219], v[64:67]
	s_setprio 0
	s_barrier
	s_add_i32 s66, s71, s94
	v_lshl_add_u64 v[212:213], v[212:213], 0, s[34:35]
	s_mov_b32 m0, s66
	ds_read_b128 v[184:187], v165 offset:49152
	ds_read_b128 v[188:191], v165 offset:50176
	ds_read_b128 v[192:195], v165 offset:51200
	ds_read_b128 v[196:199], v165 offset:52224
	ds_read_b128 v[200:203], v165 offset:53248
	ds_read_b128 v[204:207], v165 offset:54272
	ds_read_b128 v[208:211], v165 offset:55296
	ds_read_b128 v[216:219], v165 offset:56320
	global_load_lds_dwordx4 v[212:213], off
	s_add_i32 m0, s66, 0x2000
	s_add_u32 s64, s64, 0x40080
	v_lshl_add_u64 v[212:213], v[214:215], 0, s[34:35]
	s_addc_u32 s65, s65, 0
	s_add_i32 s66, s86, s94
	global_load_lds_dwordx4 v[212:213], off
	v_lshl_add_u64 v[212:213], s[64:65], 0, v[130:131]
	s_mov_b32 m0, s66
	s_nop 0
	global_load_lds_dwordx4 v[212:213], off
	v_lshl_add_u64 v[212:213], s[64:65], 0, v[134:135]
	s_add_i32 m0, s66, 0x2000
	s_nop 0
	global_load_lds_dwordx4 v[212:213], off
	v_lshl_add_u64 v[212:213], v[220:221], 0, s[34:35]
	s_mov_b32 m0, s27
	s_nop 0
	global_load_lds_dwordx4 v[212:213], off
	v_lshl_add_u64 v[212:213], v[222:223], 0, s[34:35]
	s_mov_b32 m0, s55
	s_nop 0
	global_load_lds_dwordx4 v[212:213], off
	s_waitcnt vmcnt(8)
	s_waitcnt lgkmcnt(0)
	s_barrier
	s_setprio 1
	v_mfma_f32_16x16x32_bf16 v[60:63], v[146:149], v[184:187], v[60:63]
	v_mfma_f32_16x16x32_bf16 v[56:59], v[154:157], v[184:187], v[56:59]
	v_mfma_f32_16x16x32_bf16 v[44:47], v[146:149], v[192:195], v[44:47]
	v_mfma_f32_16x16x32_bf16 v[40:43], v[154:157], v[192:195], v[40:43]
	v_mfma_f32_16x16x32_bf16 v[28:31], v[146:149], v[200:203], v[28:31]
	v_mfma_f32_16x16x32_bf16 v[24:27], v[154:157], v[200:203], v[24:27]
	v_mfma_f32_16x16x32_bf16 v[12:15], v[146:149], v[208:211], v[12:15]
	v_mfma_f32_16x16x32_bf16 v[8:11], v[154:157], v[208:211], v[8:11]
	v_mfma_f32_16x16x32_bf16 v[60:63], v[150:153], v[188:191], v[60:63]
	v_mfma_f32_16x16x32_bf16 v[56:59], v[158:161], v[188:191], v[56:59]
	v_mfma_f32_16x16x32_bf16 v[44:47], v[150:153], v[196:199], v[44:47]
	v_mfma_f32_16x16x32_bf16 v[40:43], v[158:161], v[196:199], v[40:43]
	v_mfma_f32_16x16x32_bf16 v[28:31], v[150:153], v[204:207], v[28:31]
	v_mfma_f32_16x16x32_bf16 v[24:27], v[158:161], v[204:207], v[24:27]
	v_mfma_f32_16x16x32_bf16 v[12:15], v[150:153], v[216:219], v[12:15]
	v_mfma_f32_16x16x32_bf16 v[8:11], v[158:161], v[216:219], v[8:11]
	v_mfma_f32_16x16x32_bf16 v[52:55], v[168:171], v[184:187], v[52:55]
	v_mfma_f32_16x16x32_bf16 v[48:51], v[176:179], v[184:187], v[48:51]
	v_mfma_f32_16x16x32_bf16 v[36:39], v[168:171], v[192:195], v[36:39]
	v_mfma_f32_16x16x32_bf16 v[32:35], v[176:179], v[192:195], v[32:35]
	v_mfma_f32_16x16x32_bf16 v[20:23], v[168:171], v[200:203], v[20:23]
	v_mfma_f32_16x16x32_bf16 v[16:19], v[176:179], v[200:203], v[16:19]
	v_mfma_f32_16x16x32_bf16 v[4:7], v[168:171], v[208:211], v[4:7]
	v_mfma_f32_16x16x32_bf16 v[0:3], v[176:179], v[208:211], v[0:3]
	v_mfma_f32_16x16x32_bf16 v[52:55], v[172:175], v[188:191], v[52:55]
	v_mfma_f32_16x16x32_bf16 v[48:51], v[180:183], v[188:191], v[48:51]
	v_mfma_f32_16x16x32_bf16 v[36:39], v[172:175], v[196:199], v[36:39]
	v_mfma_f32_16x16x32_bf16 v[32:35], v[180:183], v[196:199], v[32:35]
	v_mfma_f32_16x16x32_bf16 v[20:23], v[172:175], v[204:207], v[20:23]
	v_mfma_f32_16x16x32_bf16 v[16:19], v[180:183], v[204:207], v[16:19]
	v_mfma_f32_16x16x32_bf16 v[4:7], v[172:175], v[216:219], v[4:7]
	v_mfma_f32_16x16x32_bf16 v[0:3], v[180:183], v[216:219], v[0:3]
	s_setprio 0
	s_barrier
	s_add_i32 s70, s70, 2
	s_add_u32 s12, s12, 0x100
	s_addc_u32 s13, s13, 0
	s_add_u32 s68, s68, 0x100
	s_addc_u32 s69, s69, 0
	s_cmp_gt_u32 s70, 13
	s_cbranch_scc0 .LBB0_400
	s_branch .Lpeel_exit_2

; #define PG8_STAGE(bufoff, gbase, voff) do { _Pragma("unroll") for (int _i = 0; _i < 2; ++_i) \
;         __builtin_amdgcn_global_load_lds((const unsigned*)((const char*)(gbase) + (voff)[_i]), (LAS unsigned*)(lds + (bufoff) + ldsw + _i * 8192), 16, 0, 0); } while (0)
; #define PG8_LDA(dst, b, h) do { _Pragma("unroll") for (int m = 0; m < 4; ++m) _Pragma("unroll") for (int k = 0; k < 2; ++k) dst[m][k] = *(const LAS bf16x8*)(lds + PG8_SA(b, h) + aoff + m * 2048 + k * 1024); } while (0)
; #define PG8_WAIT_V(n) asm volatile("s_waitcnt vmcnt(" #n ")" ::: "memory")
; #define PG8_WAIT_L(n) asm volatile("s_waitcnt lgkmcnt(" #n ")" ::: "memory")
;     DI bool next(int i, Unit& u) const {
;         const long L = (long)i * G + c; if (L >= total) return false;
;         u.g = (int)(L / nwg); int wgid = (int)(L % nwg);
;         { const int q = nwg / NXCD, r = nwg % NXCD, xcd = wgid % NXCD, off = wgid / NXCD; wgid = (xcd < r ? xcd * (q + 1) : r * (q + 1) + (xcd - r) * q) + off; }
;         const int nig = WGM * nN, gid = wgid / nig, fm = gid * WGM, gsz = (nM - fm) < WGM ? (nM - fm) : WGM;
;         u.pm = fm + ((wgid % nig) % gsz); u.pn = (wgid % nig) / gsz; return true;
;     }
; template <class Epi>
; DI void gemm_phase(LAS unsigned char* lds, const int wid, const Gemm g, const Order& S, const Epi& E) {
;     ...
;         const bool has_next = S.next(ui + 1, nxt);
;         const char* nA = has_next ? (const char*)(g.A + (size_t)nxt.g * g.gsA + (size_t)nxt.pm * BM * g.lda) : cA;
;         const char* nB = has_next ? (const char*)(g.Bt + (size_t)nxt.g * g.gsB + (size_t)nxt.pn * BM * g.ldb) : cB;
;         for (int t = 0; t < nt; t += 2) {
;             const bool last = (t == nt - 2);
;             const char* a1 = cA + (size_t)(t + 1) * kstep;
;             const char* a2 = last ? nA : cA + (size_t)(t + 2) * kstep; const char* b2 = last ? nB : cB + (size_t)(t + 2) * kstep;
;             const char* a3 = a2 + kstep; const char* b3 = b2 + kstep;
;             PG8_LDB(B0, 0, 0); PG8_LDB(B1, 0, 1); PG8_SCHED; PG8_LDA(At, 0, 0); PG8_STAGE(PG8_SA(1, 1), a1 + hstepA, voffA);
;             PG8_WAIT_V(8); PG8_WAIT_L(0); PG8_BAR; PG8_MMA(0, 0, At, B0); PG8_MMA(0, 1, At, B1); PG8_BAR; PG8_SCHED;
;             PG8_LDA(At, 0, 1); PG8_STAGE(PG8_SB(0, 0), b2, voffB); PG8_STAGE(PG8_SB(0, 1), b2 + hstepB, voffB); PG8_STAGE(PG8_SA(0, 0), a2, voffA);
.LBB0_1333:
.LBB0_1335:
	s_add_u32 s38, s38, 0x40080
	s_addc_u32 s39, s39, 0
	s_add_u32 s58, s40, 0x100
	v_mov_b32_e32 v0, 0
	s_addc_u32 s59, s41, 0
	s_mov_b32 s60, -2
	s_lshl_b32 s65, s36, 8
	s_add_i32 s65, s65, s95
	v_mbcnt_lo_u32_b32 v244, -1, 0
	v_mbcnt_hi_u32_b32 v244, -1, v244
	v_and_or_b32 v244, v244, 15, s65
	v_ashrrev_i32_e32 v245, 31, v244
	v_lshl_add_u64 v[246:247], v[244:245], 2, s[12:13]
	global_load_dword v236, v[246:247], off
	global_load_dword v237, v[246:247], off offset:64
	global_load_dword v238, v[246:247], off offset:128
	global_load_dword v239, v[246:247], off offset:192
	global_load_dword v240, v[246:247], off offset:512
	global_load_dword v241, v[246:247], off offset:576
	global_load_dword v242, v[246:247], off offset:640
	global_load_dword v243, v[246:247], off offset:704
	ds_read_b128 v[164:167], v151
	ds_read_b128 v[168:171], v151 offset:1024
	ds_read_b128 v[172:175], v151 offset:2048
	ds_read_b128 v[176:179], v151 offset:3072
	ds_read_b128 v[180:183], v155
	ds_read_b128 v[184:187], v155 offset:1024
	ds_read_b128 v[188:191], v155 offset:2048
	ds_read_b128 v[192:195], v155 offset:3072
	s_add_u32 s40, s38, 0xfffc0080
	s_addc_u32 s41, s39, -1
	s_cmp_eq_u32 s60, 12
	s_cselect_b32 s43, s27, s41
	s_cselect_b32 s42, s56, s40
	s_cselect_b32 s41, s29, s59
	s_cselect_b32 s40, s57, s58
	v_lshl_add_u64 v[144:145], s[38:39], 0, v[136:137]
	s_add_i32 m0, s37, 0xc000
	ds_read_b128 v[196:199], v159
	ds_read_b128 v[200:203], v159 offset:1024
	ds_read_b128 v[204:207], v159 offset:2048
	ds_read_b128 v[208:211], v159 offset:3072
	ds_read_b128 v[212:215], v159 offset:4096
	ds_read_b128 v[216:219], v159 offset:5120
	ds_read_b128 v[220:223], v159 offset:6144
	ds_read_b128 v[224:227], v159 offset:7168
	global_load_lds_dwordx4 v[144:145], off
	v_lshl_add_u64 v[144:145], s[38:39], 0, v[138:139]
	s_add_i32 m0, s37, 0xe000
	s_nop 0
	global_load_lds_dwordx4 v[144:145], off
	s_waitcnt vmcnt(8)
	s_waitcnt lgkmcnt(0)
	s_barrier
	s_setprio 1
	v_mfma_f32_16x16x32_bf16 v[124:127], v[164:167], v[196:199], 0
	v_mfma_f32_16x16x32_bf16 v[120:123], v[172:175], v[196:199], 0
	v_mfma_f32_16x16x32_bf16 v[108:111], v[164:167], v[204:207], 0
	v_mfma_f32_16x16x32_bf16 v[104:107], v[172:175], v[204:207], 0
	v_mfma_f32_16x16x32_bf16 v[92:95], v[164:167], v[212:215], 0
	v_mfma_f32_16x16x32_bf16 v[88:91], v[172:175], v[212:215], 0
	v_mfma_f32_16x16x32_bf16 v[76:79], v[164:167], v[220:223], 0
	v_mfma_f32_16x16x32_bf16 v[72:75], v[172:175], v[220:223], 0
	v_mfma_f32_16x16x32_bf16 v[124:127], v[168:171], v[200:203], v[124:127]
	v_mfma_f32_16x16x32_bf16 v[120:123], v[176:179], v[200:203], v[120:123]
	v_mfma_f32_16x16x32_bf16 v[108:111], v[168:171], v[208:211], v[108:111]
	v_mfma_f32_16x16x32_bf16 v[104:107], v[176:179], v[208:211], v[104:107]
	v_mfma_f32_16x16x32_bf16 v[92:95], v[168:171], v[216:219], v[92:95]
	v_mfma_f32_16x16x32_bf16 v[88:91], v[176:179], v[216:219], v[88:91]
	v_mfma_f32_16x16x32_bf16 v[76:79], v[168:171], v[224:227], v[76:79]
	v_mfma_f32_16x16x32_bf16 v[72:75], v[176:179], v[224:227], v[72:75]
	v_mfma_f32_16x16x32_bf16 v[116:119], v[180:183], v[196:199], 0
	v_mfma_f32_16x16x32_bf16 v[112:115], v[188:191], v[196:199], 0
	v_mfma_f32_16x16x32_bf16 v[100:103], v[180:183], v[204:207], 0
	v_mfma_f32_16x16x32_bf16 v[96:99], v[188:191], v[204:207], 0
	v_mfma_f32_16x16x32_bf16 v[84:87], v[180:183], v[212:215], 0
	v_mfma_f32_16x16x32_bf16 v[80:83], v[188:191], v[212:215], 0
	v_mfma_f32_16x16x32_bf16 v[68:71], v[180:183], v[220:223], 0
	v_mfma_f32_16x16x32_bf16 v[64:67], v[188:191], v[220:223], 0
	v_mfma_f32_16x16x32_bf16 v[116:119], v[184:187], v[200:203], v[116:119]
	v_mfma_f32_16x16x32_bf16 v[112:115], v[192:195], v[200:203], v[112:115]
	v_mfma_f32_16x16x32_bf16 v[100:103], v[184:187], v[208:211], v[100:103]
	v_mfma_f32_16x16x32_bf16 v[96:99], v[192:195], v[208:211], v[96:99]
	v_mfma_f32_16x16x32_bf16 v[84:87], v[184:187], v[216:219], v[84:87]
	v_mfma_f32_16x16x32_bf16 v[80:83], v[192:195], v[216:219], v[80:83]
	v_mfma_f32_16x16x32_bf16 v[68:71], v[184:187], v[224:227], v[68:71]
	v_mfma_f32_16x16x32_bf16 v[64:67], v[192:195], v[224:227], v[64:67]
	s_setprio 0
	s_barrier
	s_add_i32 s61, s53, s94
	v_lshl_add_u64 v[144:145], s[40:41], 0, v[132:133]
	s_mov_b32 m0, s61
	ds_read_b128 v[196:199], v159 offset:16384
	ds_read_b128 v[200:203], v159 offset:17408
	ds_read_b128 v[204:207], v159 offset:18432
	ds_read_b128 v[208:211], v159 offset:19456
	ds_read_b128 v[212:215], v159 offset:20480
	ds_read_b128 v[216:219], v159 offset:21504
	ds_read_b128 v[220:223], v159 offset:22528
	ds_read_b128 v[224:227], v159 offset:23552
	global_load_lds_dwordx4 v[144:145], off
	s_add_i32 m0, s61, 0x2000
	s_add_u32 s62, s40, 0x40000
	v_lshl_add_u64 v[148:149], s[40:41], 0, v[128:129]
	s_addc_u32 s63, s41, 0
	s_add_i32 s61, s54, s94
	global_load_lds_dwordx4 v[148:149], off
	v_lshl_add_u64 v[152:153], s[62:63], 0, v[132:133]
	s_mov_b32 m0, s61
	v_lshl_add_u64 v[156:157], s[42:43], 0, v[130:131]
	global_load_lds_dwordx4 v[152:153], off
	v_lshl_add_u64 v[152:153], s[62:63], 0, v[128:129]
	s_add_i32 m0, s61, 0x2000
	s_nop 0
	global_load_lds_dwordx4 v[152:153], off
	v_lshl_add_u64 v[152:153], s[42:43], 0, v[134:135]
	s_mov_b32 m0, s37
	s_nop 0
	global_load_lds_dwordx4 v[152:153], off
	s_mov_b32 m0, s46
	s_nop 0
	global_load_lds_dwordx4 v[156:157], off
	s_add_i32 s50, s50, 1
	s_mul_i32 s8, s50, s33
	s_mul_hi_u32 s9, s50, s64
	s_add_i32 s9, s9, s8
	s_mul_i32 s8, s50, s64
	s_add_u32 s30, s8, s2
	s_addc_u32 s31, s9, s3
	v_cmp_lt_i64_e64 s[8:9], s[30:31], v[140:141]
	s_mul_i32 s29, s31, 0xba2e8ba3
	s_mul_hi_u32 s34, s30, 0xba2e8ba3
	s_mul_hi_u32 s28, s31, 0xba2e8ba3
	s_add_u32 s29, s29, s34
	s_mul_i32 s27, s30, 0x2e8ba2e8
	s_addc_u32 s28, s28, 0
	s_mul_hi_u32 s26, s30, 0x2e8ba2e8
	s_add_u32 s27, s27, s29
	s_addc_u32 s26, s26, 0
	s_add_u32 s26, s28, s26
	s_addc_u32 s27, 0, 0
	s_mul_i32 s29, s31, 0x2e8ba2e8
	s_mul_hi_u32 s28, s31, 0x2e8ba2e8
	s_add_u32 s26, s29, s26
	s_addc_u32 s27, s28, s27
	s_ashr_i32 s28, s31, 31
	s_mul_i32 s29, s28, 0x2e8ba2e8
	s_mul_hi_u32 s31, s28, 0xba2e8ba3
	s_add_i32 s29, s31, s29
	s_mul_i32 s28, s28, 0xba2e8ba3
	s_add_i32 s29, s29, s28
	s_add_u32 s26, s26, s28
	s_addc_u32 s27, s27, s29
	s_ashr_i64 s[28:29], s[26:27], 10
	s_lshr_b32 s26, s27, 31
	s_add_u32 s26, s28, s26
	s_mulk_i32 s26, 0x1600
	s_sub_i32 s26, s30, s26
	s_sext_i32_i16 s27, s26
	s_bfe_u32 s27, s27, 0x3001c
	s_add_i32 s27, s26, s27
	s_waitcnt vmcnt(8)
	s_waitcnt lgkmcnt(0)
	s_barrier
; #define PG8_STAGE(bufoff, gbase, voff) do { _Pragma("unroll") for (int _i = 0; _i < 2; ++_i) \
;         __builtin_amdgcn_global_load_lds((const unsigned*)((const char*)(gbase) + (voff)[_i]), (LAS unsigned*)(lds + (bufoff) + ldsw + _i * 8192), 16, 0, 0); } while (0)
; #define PG8_LDA(dst, b, h) do { _Pragma("unroll") for (int m = 0; m < 4; ++m) _Pragma("unroll") for (int k = 0; k < 2; ++k) dst[m][k] = *(const LAS bf16x8*)(lds + PG8_SA(b, h) + aoff + m * 2048 + k * 1024); } while (0)
; #define PG8_LDB(dst, b, h) do { _Pragma("unroll") for (int n = 0; n < 2; ++n) _Pragma("unroll") for (int k = 0; k < 2; ++k) dst[n][k] = *(const LAS bf16x8*)(lds + PG8_SB(b, h) + boff + n * 2048 + k * 1024); } while (0)
; #define PG8_MMA(ai, bj, At, Bt) do { __builtin_amdgcn_s_setprio(1); _Pragma("unroll") for (int m = 0; m < 4; ++m) _Pragma("unroll") for (int n = 0; n < 2; ++n) _Pragma("unroll") for (int k = 0; k < 2; ++k) \
;         acc[ai][bj][m][n] = __builtin_amdgcn_mfma_f32_16x16x32_bf16(Bt[n][k], At[m][k], acc[ai][bj][m][n], 0, 0, 0); __builtin_amdgcn_s_setprio(0); } while (0)
; #define PG8_WAIT_V(n) asm volatile("s_waitcnt vmcnt(" #n ")" ::: "memory")
; #define PG8_WAIT_L(n) asm volatile("s_waitcnt lgkmcnt(" #n ")" ::: "memory")
; #define PG8_BAR __builtin_amdgcn_s_barrier()
; #define PG8_SCHED __builtin_amdgcn_sched_barrier(0)
;     DI bool next(int i, Unit& u) const {
;     ...
;         { const int q = nwg / NXCD, r = nwg % NXCD, xcd = wgid % NXCD, off = wgid / NXCD; wgid = (xcd < r ? xcd * (q + 1) : r * (q + 1) + (xcd - r) * q) + off; }
;         const int nig = WGM * nN, gid = wgid / nig, fm = gid * WGM, gsz = (nM - fm) < WGM ? (nM - fm) : WGM;
;         u.pm = fm + ((wgid % nig) % gsz); u.pn = (wgid % nig) / gsz; return true;
; template <class Epi>
; DI void gemm_phase(LAS unsigned char* lds, const int wid, const Gemm g, const Order& S, const Epi& E) {
;     ...
;         const char* nA = has_next ? (const char*)(g.A + (size_t)nxt.g * g.gsA + (size_t)nxt.pm * BM * g.lda) : cA;
;         const char* nB = has_next ? (const char*)(g.Bt + (size_t)nxt.g * g.gsB + (size_t)nxt.pn * BM * g.ldb) : cB;
;     ...
;             PG8_WAIT_V(8); PG8_WAIT_L(0); PG8_BAR; PG8_MMA(1, 0, At, B0); PG8_MMA(1, 1, At, B1); PG8_BAR; PG8_SCHED;
;             PG8_LDB(B0, 1, 0); PG8_LDB(B1, 1, 1); PG8_SCHED; PG8_LDA(At, 1, 0); PG8_STAGE(PG8_SA(0, 1), a2 + hstepA, voffA);
	s_setprio 1
	v_mfma_f32_16x16x32_bf16 v[60:63], v[164:167], v[196:199], 0
	v_mfma_f32_16x16x32_bf16 v[56:59], v[172:175], v[196:199], 0
	v_mfma_f32_16x16x32_bf16 v[44:47], v[164:167], v[204:207], 0
	v_mfma_f32_16x16x32_bf16 v[40:43], v[172:175], v[204:207], 0
	v_mfma_f32_16x16x32_bf16 v[28:31], v[164:167], v[212:215], 0
	v_mfma_f32_16x16x32_bf16 v[24:27], v[172:175], v[212:215], 0
	v_mfma_f32_16x16x32_bf16 v[12:15], v[164:167], v[220:223], 0
	v_mfma_f32_16x16x32_bf16 v[8:11], v[172:175], v[220:223], 0
	v_mfma_f32_16x16x32_bf16 v[60:63], v[168:171], v[200:203], v[60:63]
	v_mfma_f32_16x16x32_bf16 v[56:59], v[176:179], v[200:203], v[56:59]
	v_mfma_f32_16x16x32_bf16 v[44:47], v[168:171], v[208:211], v[44:47]
	v_mfma_f32_16x16x32_bf16 v[40:43], v[176:179], v[208:211], v[40:43]
	v_mfma_f32_16x16x32_bf16 v[28:31], v[168:171], v[216:219], v[28:31]
	v_mfma_f32_16x16x32_bf16 v[24:27], v[176:179], v[216:219], v[24:27]
	v_mfma_f32_16x16x32_bf16 v[12:15], v[168:171], v[224:227], v[12:15]
	v_mfma_f32_16x16x32_bf16 v[8:11], v[176:179], v[224:227], v[8:11]
	v_mfma_f32_16x16x32_bf16 v[52:55], v[180:183], v[196:199], 0
	v_mfma_f32_16x16x32_bf16 v[48:51], v[188:191], v[196:199], 0
	v_mfma_f32_16x16x32_bf16 v[36:39], v[180:183], v[204:207], 0
	v_mfma_f32_16x16x32_bf16 v[32:35], v[188:191], v[204:207], 0
	v_mfma_f32_16x16x32_bf16 v[20:23], v[180:183], v[212:215], 0
	v_mfma_f32_16x16x32_bf16 v[16:19], v[188:191], v[212:215], 0
	v_mfma_f32_16x16x32_bf16 v[4:7], v[180:183], v[220:223], 0
	v_mfma_f32_16x16x32_bf16 v[0:3], v[188:191], v[220:223], 0
	v_mfma_f32_16x16x32_bf16 v[52:55], v[184:187], v[200:203], v[52:55]
	v_mfma_f32_16x16x32_bf16 v[48:51], v[192:195], v[200:203], v[48:51]
	v_mfma_f32_16x16x32_bf16 v[36:39], v[184:187], v[208:211], v[36:39]
	v_mfma_f32_16x16x32_bf16 v[32:35], v[192:195], v[208:211], v[32:35]
	v_mfma_f32_16x16x32_bf16 v[20:23], v[184:187], v[216:219], v[20:23]
	v_mfma_f32_16x16x32_bf16 v[16:19], v[192:195], v[216:219], v[16:19]
	v_mfma_f32_16x16x32_bf16 v[4:7], v[184:187], v[224:227], v[4:7]
	v_mfma_f32_16x16x32_bf16 v[0:3], v[192:195], v[224:227], v[0:3]
	s_setprio 0
	s_barrier
	s_add_i32 s61, 0, 0x18000
	v_add_u32_e32 v146, s61, v147
	s_add_i32 s62, 0, 0x1c000
	ds_read_b128 v[164:167], v146
	ds_read_b128 v[168:171], v146 offset:1024
	ds_read_b128 v[172:175], v146 offset:2048
	ds_read_b128 v[176:179], v146 offset:3072
	v_add_u32_e32 v146, s62, v147
	ds_read_b128 v[180:183], v146
	ds_read_b128 v[184:187], v146 offset:1024
	ds_read_b128 v[188:191], v146 offset:2048
	ds_read_b128 v[192:195], v146 offset:3072
	s_add_u32 s42, s42, 0x40000
	s_addc_u32 s43, s43, 0
	s_mov_b32 m0, s47
	v_lshl_add_u64 v[160:161], s[42:43], 0, v[134:135]
	ds_read_b128 v[196:199], v159 offset:32768
	ds_read_b128 v[200:203], v159 offset:33792
	ds_read_b128 v[204:207], v159 offset:34816
	ds_read_b128 v[208:211], v159 offset:35840
	ds_read_b128 v[212:215], v159 offset:36864
	ds_read_b128 v[216:219], v159 offset:37888
	ds_read_b128 v[220:223], v159 offset:38912
	ds_read_b128 v[224:227], v159 offset:39936
	global_load_lds_dwordx4 v[160:161], off
	v_lshl_add_u64 v[160:161], s[42:43], 0, v[130:131]
	s_mov_b32 m0, s48
	s_nop 0
	global_load_lds_dwordx4 v[160:161], off
	s_sext_i32_i16 s28, s27
	s_and_b32 s27, s27, 0xfff8
	s_sub_i32 s26, s26, s27
	s_ashr_i32 s28, s28, 3
	s_sext_i32_i16 s27, s26
	s_cmp_lt_i32 s27, 0
	s_cselect_b32 s27, s45, 0x2c0
	s_mul_i32 s26, s26, s27
	s_add_i32 s26, s26, s28
	s_sext_i32_i16 s27, s26
	s_mulk_i32 s27, 0xba3
	s_lshr_b32 s28, s27, 31
	s_ashr_i32 s27, s27, 19
	s_add_i32 s27, s27, s28
	s_lshl_b32 s28, s27, 3
	s_mulk_i32 s27, 0xb0
	s_sub_i32 s26, s26, s27
	s_sext_i32_i16 s27, s26
	s_bfe_u32 s27, s27, 0x3001c
	s_add_i32 s27, s26, s27
	s_sext_i32_i16 s29, s27
	s_and_b32 s27, s27, 0xfff8
	s_sub_i32 s26, s26, s27
	s_sext_i32_i16 s26, s26
	s_add_i32 s26, s28, s26
	s_ashr_i32 s28, s29, 3
	s_ashr_i32 s27, s26, 31
	s_lshl_b64 s[30:31], s[26:27], 19
	s_add_u32 s30, s6, s30
	s_addc_u32 s31, s7, s31
	s_and_b64 s[34:35], s[8:9], exec
	s_cselect_b32 s27, s31, s39
	s_cselect_b32 s56, s30, s38
	s_ashr_i32 s29, s28, 31
	s_lshl_b64 s[34:35], s[28:29], 19
	s_add_u32 s34, s21, s34
	s_addc_u32 s35, s44, s35
	s_and_b64 vcc, s[8:9], exec
	s_cselect_b32 s29, s35, s41
	s_cselect_b32 s57, s34, s40
	s_waitcnt vmcnt(8)
	s_waitcnt lgkmcnt(0)
	s_barrier
; #define PG8_STAGE(bufoff, gbase, voff) do { _Pragma("unroll") for (int _i = 0; _i < 2; ++_i) \
;         __builtin_amdgcn_global_load_lds((const unsigned*)((const char*)(gbase) + (voff)[_i]), (LAS unsigned*)(lds + (bufoff) + ldsw + _i * 8192), 16, 0, 0); } while (0)
; #define PG8_LDA(dst, b, h) do { _Pragma("unroll") for (int m = 0; m < 4; ++m) _Pragma("unroll") for (int k = 0; k < 2; ++k) dst[m][k] = *(const LAS bf16x8*)(lds + PG8_SA(b, h) + aoff + m * 2048 + k * 1024); } while (0)
; #define PG8_MMA(ai, bj, At, Bt) do { __builtin_amdgcn_s_setprio(1); _Pragma("unroll") for (int m = 0; m < 4; ++m) _Pragma("unroll") for (int n = 0; n < 2; ++n) _Pragma("unroll") for (int k = 0; k < 2; ++k) \
;         acc[ai][bj][m][n] = __builtin_amdgcn_mfma_f32_16x16x32_bf16(Bt[n][k], At[m][k], acc[ai][bj][m][n], 0, 0, 0); __builtin_amdgcn_s_setprio(0); } while (0)
; #define PG8_WAIT_V(n) asm volatile("s_waitcnt vmcnt(" #n ")" ::: "memory")
; #define PG8_WAIT_L(n) asm volatile("s_waitcnt lgkmcnt(" #n ")" ::: "memory")
; #define PG8_BAR __builtin_amdgcn_s_barrier()
; #define PG8_SCHED __builtin_amdgcn_sched_barrier(0)
; template <class Epi>
; DI void gemm_phase(LAS unsigned char* lds, const int wid, const Gemm g, const Order& S, const Epi& E) {
;     ...
;             PG8_WAIT_V(8); PG8_WAIT_L(0); PG8_BAR; PG8_MMA(0, 0, At, B0); PG8_MMA(0, 1, At, B1); PG8_BAR; PG8_SCHED;
;             PG8_LDA(At, 1, 1); PG8_STAGE(PG8_SB(1, 0), b3, voffB); PG8_STAGE(PG8_SB(1, 1), b3 + hstepB, voffB); PG8_STAGE(PG8_SA(1, 0), a3, voffA);
;             PG8_WAIT_V(8); PG8_WAIT_L(0); PG8_BAR; PG8_MMA(1, 0, At, B0); PG8_MMA(1, 1, At, B1); PG8_BAR; PG8_SCHED;
	s_setprio 1
	v_mfma_f32_16x16x32_bf16 v[124:127], v[164:167], v[196:199], v[124:127]
	v_mfma_f32_16x16x32_bf16 v[120:123], v[172:175], v[196:199], v[120:123]
	v_mfma_f32_16x16x32_bf16 v[108:111], v[164:167], v[204:207], v[108:111]
	v_mfma_f32_16x16x32_bf16 v[104:107], v[172:175], v[204:207], v[104:107]
	v_mfma_f32_16x16x32_bf16 v[92:95], v[164:167], v[212:215], v[92:95]
	v_mfma_f32_16x16x32_bf16 v[88:91], v[172:175], v[212:215], v[88:91]
	v_mfma_f32_16x16x32_bf16 v[76:79], v[164:167], v[220:223], v[76:79]
	v_mfma_f32_16x16x32_bf16 v[72:75], v[172:175], v[220:223], v[72:75]
	v_mfma_f32_16x16x32_bf16 v[124:127], v[168:171], v[200:203], v[124:127]
	v_mfma_f32_16x16x32_bf16 v[120:123], v[176:179], v[200:203], v[120:123]
	v_mfma_f32_16x16x32_bf16 v[108:111], v[168:171], v[208:211], v[108:111]
	v_mfma_f32_16x16x32_bf16 v[104:107], v[176:179], v[208:211], v[104:107]
	v_mfma_f32_16x16x32_bf16 v[92:95], v[168:171], v[216:219], v[92:95]
	v_mfma_f32_16x16x32_bf16 v[88:91], v[176:179], v[216:219], v[88:91]
	v_mfma_f32_16x16x32_bf16 v[76:79], v[168:171], v[224:227], v[76:79]
	v_mfma_f32_16x16x32_bf16 v[72:75], v[176:179], v[224:227], v[72:75]
	v_mfma_f32_16x16x32_bf16 v[116:119], v[180:183], v[196:199], v[116:119]
	v_mfma_f32_16x16x32_bf16 v[112:115], v[188:191], v[196:199], v[112:115]
	v_mfma_f32_16x16x32_bf16 v[100:103], v[180:183], v[204:207], v[100:103]
	v_mfma_f32_16x16x32_bf16 v[96:99], v[188:191], v[204:207], v[96:99]
	v_mfma_f32_16x16x32_bf16 v[84:87], v[180:183], v[212:215], v[84:87]
	v_mfma_f32_16x16x32_bf16 v[80:83], v[188:191], v[212:215], v[80:83]
	v_mfma_f32_16x16x32_bf16 v[68:71], v[180:183], v[220:223], v[68:71]
	v_mfma_f32_16x16x32_bf16 v[64:67], v[188:191], v[220:223], v[64:67]
	v_mfma_f32_16x16x32_bf16 v[116:119], v[184:187], v[200:203], v[116:119]
	v_mfma_f32_16x16x32_bf16 v[112:115], v[192:195], v[200:203], v[112:115]
	v_mfma_f32_16x16x32_bf16 v[100:103], v[184:187], v[208:211], v[100:103]
	v_mfma_f32_16x16x32_bf16 v[96:99], v[192:195], v[208:211], v[96:99]
	v_mfma_f32_16x16x32_bf16 v[84:87], v[184:187], v[216:219], v[84:87]
	v_mfma_f32_16x16x32_bf16 v[80:83], v[192:195], v[216:219], v[80:83]
	v_mfma_f32_16x16x32_bf16 v[68:71], v[184:187], v[224:227], v[68:71]
	v_mfma_f32_16x16x32_bf16 v[64:67], v[192:195], v[224:227], v[64:67]
	s_setprio 0
	s_barrier
	s_add_i32 s42, s61, s94
	v_lshl_add_u64 v[144:145], v[144:145], 0, s[16:17]
	s_mov_b32 m0, s42
	ds_read_b128 v[196:199], v159 offset:49152
	ds_read_b128 v[200:203], v159 offset:50176
	ds_read_b128 v[204:207], v159 offset:51200
	ds_read_b128 v[208:211], v159 offset:52224
	ds_read_b128 v[212:215], v159 offset:53248
	ds_read_b128 v[216:219], v159 offset:54272
	ds_read_b128 v[220:223], v159 offset:55296
	ds_read_b128 v[224:227], v159 offset:56320
	global_load_lds_dwordx4 v[144:145], off
	s_add_i32 m0, s42, 0x2000
	s_add_u32 s40, s40, 0x40080
	v_lshl_add_u64 v[144:145], v[148:149], 0, s[16:17]
	s_addc_u32 s41, s41, 0
	s_add_i32 s42, s62, s94
	global_load_lds_dwordx4 v[144:145], off
	v_lshl_add_u64 v[144:145], s[40:41], 0, v[132:133]
	s_mov_b32 m0, s42
	s_nop 0
	global_load_lds_dwordx4 v[144:145], off
	v_lshl_add_u64 v[144:145], s[40:41], 0, v[128:129]
	s_add_i32 m0, s42, 0x2000
	s_nop 0
	global_load_lds_dwordx4 v[144:145], off
	v_lshl_add_u64 v[144:145], v[152:153], 0, s[16:17]
	s_mov_b32 m0, s51
	s_nop 0
	global_load_lds_dwordx4 v[144:145], off
	v_lshl_add_u64 v[144:145], v[156:157], 0, s[16:17]
	s_mov_b32 m0, s52
	s_nop 0
	global_load_lds_dwordx4 v[144:145], off
	s_waitcnt vmcnt(8)
	s_waitcnt lgkmcnt(0)
	s_barrier
	s_setprio 1
	v_mfma_f32_16x16x32_bf16 v[60:63], v[164:167], v[196:199], v[60:63]
	v_mfma_f32_16x16x32_bf16 v[56:59], v[172:175], v[196:199], v[56:59]
	v_mfma_f32_16x16x32_bf16 v[44:47], v[164:167], v[204:207], v[44:47]
	v_mfma_f32_16x16x32_bf16 v[40:43], v[172:175], v[204:207], v[40:43]
	v_mfma_f32_16x16x32_bf16 v[28:31], v[164:167], v[212:215], v[28:31]
	v_mfma_f32_16x16x32_bf16 v[24:27], v[172:175], v[212:215], v[24:27]
	v_mfma_f32_16x16x32_bf16 v[12:15], v[164:167], v[220:223], v[12:15]
	v_mfma_f32_16x16x32_bf16 v[8:11], v[172:175], v[220:223], v[8:11]
	v_mfma_f32_16x16x32_bf16 v[60:63], v[168:171], v[200:203], v[60:63]
	v_mfma_f32_16x16x32_bf16 v[56:59], v[176:179], v[200:203], v[56:59]
	v_mfma_f32_16x16x32_bf16 v[44:47], v[168:171], v[208:211], v[44:47]
	v_mfma_f32_16x16x32_bf16 v[40:43], v[176:179], v[208:211], v[40:43]
	v_mfma_f32_16x16x32_bf16 v[28:31], v[168:171], v[216:219], v[28:31]
	v_mfma_f32_16x16x32_bf16 v[24:27], v[176:179], v[216:219], v[24:27]
	v_mfma_f32_16x16x32_bf16 v[12:15], v[168:171], v[224:227], v[12:15]
	v_mfma_f32_16x16x32_bf16 v[8:11], v[176:179], v[224:227], v[8:11]
	v_mfma_f32_16x16x32_bf16 v[52:55], v[180:183], v[196:199], v[52:55]
	v_mfma_f32_16x16x32_bf16 v[48:51], v[188:191], v[196:199], v[48:51]
	v_mfma_f32_16x16x32_bf16 v[36:39], v[180:183], v[204:207], v[36:39]
	v_mfma_f32_16x16x32_bf16 v[32:35], v[188:191], v[204:207], v[32:35]
	v_mfma_f32_16x16x32_bf16 v[20:23], v[180:183], v[212:215], v[20:23]
	v_mfma_f32_16x16x32_bf16 v[16:19], v[188:191], v[212:215], v[16:19]
	v_mfma_f32_16x16x32_bf16 v[4:7], v[180:183], v[220:223], v[4:7]
	v_mfma_f32_16x16x32_bf16 v[0:3], v[188:191], v[220:223], v[0:3]
	v_mfma_f32_16x16x32_bf16 v[52:55], v[184:187], v[200:203], v[52:55]
	v_mfma_f32_16x16x32_bf16 v[48:51], v[192:195], v[200:203], v[48:51]
	v_mfma_f32_16x16x32_bf16 v[36:39], v[184:187], v[208:211], v[36:39]
	v_mfma_f32_16x16x32_bf16 v[32:35], v[192:195], v[208:211], v[32:35]
	v_mfma_f32_16x16x32_bf16 v[20:23], v[184:187], v[216:219], v[20:23]
	v_mfma_f32_16x16x32_bf16 v[16:19], v[192:195], v[216:219], v[16:19]
	v_mfma_f32_16x16x32_bf16 v[4:7], v[184:187], v[224:227], v[4:7]
	v_mfma_f32_16x16x32_bf16 v[0:3], v[192:195], v[224:227], v[0:3]
	s_setprio 0
	s_barrier
	s_add_i32 s60, s60, 2
	s_add_u32 s38, s38, 0x100
	s_addc_u32 s39, s39, 0
	s_add_u32 s58, s58, 0x100
	s_addc_u32 s59, s59, 0
	s_cmp_gt_u32 s60, 13
	s_cbranch_scc0 .LBB0_1336
	s_branch .Lpeel_exit_9
